# GEMM MFMA blocks reordered (bit-exact): per 16-MFMA block n-major, m, k-innermost so the two k-steps of each accumulator issue back-to-back; plus earlier mid LDS fix and no setprio flips
# speedup vs baseline: 1.0176x; 1.0128x over previous
.LBB0_177:
	ds_read_b128 v[164:167], v153
	ds_read_b128 v[168:171], v153 offset:1024
	ds_read_b128 v[172:175], v153 offset:2048
	ds_read_b128 v[176:179], v153 offset:3072
	ds_read_b128 v[184:187], v160
	ds_read_b128 v[188:191], v160 offset:1024
	ds_read_b128 v[192:195], v160 offset:2048
	ds_read_b128 v[196:199], v160 offset:3072
	s_add_u32 s28, s26, 0xfff00080
	s_addc_u32 s29, s27, -1
	s_cmp_eq_u32 s80, 60
	s_cselect_b32 s31, s19, s29
	s_cselect_b32 s30, s58, s28
	s_cselect_b32 s29, s17, s63
	s_cselect_b32 s28, s59, s62
	v_lshl_add_u64 v[148:149], s[26:27], 0, v[140:141]
	s_add_i32 m0, s25, 0xc000
	ds_read_b128 v[200:203], v161
	ds_read_b128 v[204:207], v161 offset:1024
	ds_read_b128 v[208:211], v161 offset:2048
	ds_read_b128 v[212:215], v161 offset:3072
	ds_read_b128 v[216:219], v161 offset:4096
	ds_read_b128 v[220:223], v161 offset:5120
	ds_read_b128 v[224:227], v161 offset:6144
	ds_read_b128 v[228:231], v161 offset:7168
	global_load_lds_dwordx4 v[148:149], off
	v_lshl_add_u64 v[148:149], s[26:27], 0, v[142:143]
	s_add_i32 m0, s25, 0xe000
	s_nop 0
	global_load_lds_dwordx4 v[148:149], off
	s_waitcnt vmcnt(8)
	s_waitcnt lgkmcnt(0)
	s_barrier
	s_waitcnt lgkmcnt(0)
	v_mfma_f32_16x16x32_bf16 v[126:129], v[164:167], v[200:203], v[126:129]
	v_mfma_f32_16x16x32_bf16 v[126:129], v[168:171], v[204:207], v[126:129]
	v_mfma_f32_16x16x32_bf16 v[118:121], v[164:167], v[208:211], v[118:121]
	v_mfma_f32_16x16x32_bf16 v[118:121], v[168:171], v[212:215], v[118:121]
	v_mfma_f32_16x16x32_bf16 v[102:105], v[164:167], v[216:219], v[102:105]
	v_mfma_f32_16x16x32_bf16 v[102:105], v[168:171], v[220:223], v[102:105]
	v_mfma_f32_16x16x32_bf16 v[86:89], v[164:167], v[224:227], v[86:89]
	v_mfma_f32_16x16x32_bf16 v[86:89], v[168:171], v[228:231], v[86:89]
	v_mfma_f32_16x16x32_bf16 v[122:125], v[172:175], v[200:203], v[122:125]
	v_mfma_f32_16x16x32_bf16 v[122:125], v[176:179], v[204:207], v[122:125]
	v_mfma_f32_16x16x32_bf16 v[110:113], v[172:175], v[208:211], v[110:113]
	v_mfma_f32_16x16x32_bf16 v[110:113], v[176:179], v[212:215], v[110:113]
	v_mfma_f32_16x16x32_bf16 v[94:97], v[172:175], v[216:219], v[94:97]
	v_mfma_f32_16x16x32_bf16 v[94:97], v[176:179], v[220:223], v[94:97]
	v_mfma_f32_16x16x32_bf16 v[78:81], v[172:175], v[224:227], v[78:81]
	v_mfma_f32_16x16x32_bf16 v[78:81], v[176:179], v[228:231], v[78:81]
	v_mfma_f32_16x16x32_bf16 v[114:117], v[184:187], v[200:203], v[114:117]
	v_mfma_f32_16x16x32_bf16 v[114:117], v[188:191], v[204:207], v[114:117]
	v_mfma_f32_16x16x32_bf16 v[98:101], v[184:187], v[208:211], v[98:101]
	v_mfma_f32_16x16x32_bf16 v[98:101], v[188:191], v[212:215], v[98:101]
	v_mfma_f32_16x16x32_bf16 v[82:85], v[184:187], v[216:219], v[82:85]
	v_mfma_f32_16x16x32_bf16 v[82:85], v[188:191], v[220:223], v[82:85]
	v_mfma_f32_16x16x32_bf16 v[70:73], v[184:187], v[224:227], v[70:73]
	v_mfma_f32_16x16x32_bf16 v[70:73], v[188:191], v[228:231], v[70:73]
	v_mfma_f32_16x16x32_bf16 v[106:109], v[192:195], v[200:203], v[106:109]
	v_mfma_f32_16x16x32_bf16 v[106:109], v[196:199], v[204:207], v[106:109]
	v_mfma_f32_16x16x32_bf16 v[90:93], v[192:195], v[208:211], v[90:93]
	v_mfma_f32_16x16x32_bf16 v[90:93], v[196:199], v[212:215], v[90:93]
	v_mfma_f32_16x16x32_bf16 v[74:77], v[192:195], v[216:219], v[74:77]
	v_mfma_f32_16x16x32_bf16 v[74:77], v[196:199], v[220:223], v[74:77]
	v_mfma_f32_16x16x32_bf16 v[66:69], v[192:195], v[224:227], v[66:69]
	v_mfma_f32_16x16x32_bf16 v[66:69], v[196:199], v[228:231], v[66:69]
	s_barrier
	s_add_i32 s81, s51, s34
	v_lshl_add_u64 v[148:149], s[28:29], 0, v[132:133]
	s_mov_b32 m0, s81
	ds_read_b128 v[200:203], v161 offset:16384
	ds_read_b128 v[204:207], v161 offset:17408
	ds_read_b128 v[208:211], v161 offset:18432
	ds_read_b128 v[212:215], v161 offset:19456
	ds_read_b128 v[216:219], v161 offset:20480
	ds_read_b128 v[220:223], v161 offset:21504
	ds_read_b128 v[224:227], v161 offset:22528
	ds_read_b128 v[228:231], v161 offset:23552
	global_load_lds_dwordx4 v[148:149], off
	s_add_i32 m0, s81, 0x2000
	s_add_u32 s82, s28, 0x100000
	v_lshl_add_u64 v[180:181], s[28:29], 0, v[136:137]
	s_addc_u32 s83, s29, 0
	s_add_i32 s81, s52, s34
	global_load_lds_dwordx4 v[180:181], off
	v_lshl_add_u64 v[232:233], s[82:83], 0, v[132:133]
	s_mov_b32 m0, s81
	v_lshl_add_u64 v[234:235], s[30:31], 0, v[134:135]
	global_load_lds_dwordx4 v[232:233], off
	v_lshl_add_u64 v[232:233], s[82:83], 0, v[136:137]
	s_add_i32 m0, s81, 0x2000
	s_nop 0
	global_load_lds_dwordx4 v[232:233], off
	v_lshl_add_u64 v[232:233], s[30:31], 0, v[130:131]
	s_mov_b32 m0, s25
	s_nop 0
	global_load_lds_dwordx4 v[232:233], off
	s_mov_b32 m0, s43
	s_nop 0
	global_load_lds_dwordx4 v[234:235], off
	s_waitcnt vmcnt(8)
	s_waitcnt lgkmcnt(0)
	s_barrier
	s_waitcnt lgkmcnt(0)
	v_mfma_f32_16x16x32_bf16 v[62:65], v[164:167], v[200:203], v[62:65]
	v_mfma_f32_16x16x32_bf16 v[62:65], v[168:171], v[204:207], v[62:65]
	v_mfma_f32_16x16x32_bf16 v[54:57], v[164:167], v[208:211], v[54:57]
	v_mfma_f32_16x16x32_bf16 v[54:57], v[168:171], v[212:215], v[54:57]
	v_mfma_f32_16x16x32_bf16 v[38:41], v[164:167], v[216:219], v[38:41]
	v_mfma_f32_16x16x32_bf16 v[38:41], v[168:171], v[220:223], v[38:41]
	v_mfma_f32_16x16x32_bf16 v[22:25], v[164:167], v[224:227], v[22:25]
	v_mfma_f32_16x16x32_bf16 v[22:25], v[168:171], v[228:231], v[22:25]
	v_mfma_f32_16x16x32_bf16 v[58:61], v[172:175], v[200:203], v[58:61]
	v_mfma_f32_16x16x32_bf16 v[58:61], v[176:179], v[204:207], v[58:61]
	v_mfma_f32_16x16x32_bf16 v[46:49], v[172:175], v[208:211], v[46:49]
	v_mfma_f32_16x16x32_bf16 v[46:49], v[176:179], v[212:215], v[46:49]
	v_mfma_f32_16x16x32_bf16 v[30:33], v[172:175], v[216:219], v[30:33]
	v_mfma_f32_16x16x32_bf16 v[30:33], v[176:179], v[220:223], v[30:33]
	v_mfma_f32_16x16x32_bf16 v[14:17], v[172:175], v[224:227], v[14:17]
	v_mfma_f32_16x16x32_bf16 v[14:17], v[176:179], v[228:231], v[14:17]
	v_mfma_f32_16x16x32_bf16 v[50:53], v[184:187], v[200:203], v[50:53]
	v_mfma_f32_16x16x32_bf16 v[50:53], v[188:191], v[204:207], v[50:53]
	v_mfma_f32_16x16x32_bf16 v[34:37], v[184:187], v[208:211], v[34:37]
	v_mfma_f32_16x16x32_bf16 v[34:37], v[188:191], v[212:215], v[34:37]
	v_mfma_f32_16x16x32_bf16 v[18:21], v[184:187], v[216:219], v[18:21]
	v_mfma_f32_16x16x32_bf16 v[18:21], v[188:191], v[220:223], v[18:21]
	v_mfma_f32_16x16x32_bf16 v[6:9], v[184:187], v[224:227], v[6:9]
	v_mfma_f32_16x16x32_bf16 v[6:9], v[188:191], v[228:231], v[6:9]
	v_mfma_f32_16x16x32_bf16 v[42:45], v[192:195], v[200:203], v[42:45]
	v_mfma_f32_16x16x32_bf16 v[42:45], v[196:199], v[204:207], v[42:45]
	v_mfma_f32_16x16x32_bf16 v[26:29], v[192:195], v[208:211], v[26:29]
	v_mfma_f32_16x16x32_bf16 v[26:29], v[196:199], v[212:215], v[26:29]
	v_mfma_f32_16x16x32_bf16 v[10:13], v[192:195], v[216:219], v[10:13]
	v_mfma_f32_16x16x32_bf16 v[10:13], v[196:199], v[220:223], v[10:13]
	v_mfma_f32_16x16x32_bf16 v[2:5], v[192:195], v[224:227], v[2:5]
	v_mfma_f32_16x16x32_bf16 v[2:5], v[196:199], v[228:231], v[2:5]
	s_barrier
	s_add_i32 s81, 0, 0x18000
	v_add_u32_e32 v162, s81, v151
	s_add_i32 s82, 0, 0x1c000
	ds_read_b128 v[164:167], v162
	ds_read_b128 v[168:171], v162 offset:1024
	ds_read_b128 v[172:175], v162 offset:2048
	ds_read_b128 v[176:179], v162 offset:3072
	v_add_u32_e32 v162, s82, v151
	ds_read_b128 v[184:187], v162
	ds_read_b128 v[188:191], v162 offset:1024
	ds_read_b128 v[192:195], v162 offset:2048
	ds_read_b128 v[196:199], v162 offset:3072
	s_add_u32 s30, s30, 0x100000
	s_addc_u32 s31, s31, 0
	s_mov_b32 m0, s44
	v_lshl_add_u64 v[236:237], s[30:31], 0, v[130:131]
	ds_read_b128 v[200:203], v161 offset:32768
	ds_read_b128 v[204:207], v161 offset:33792
	ds_read_b128 v[208:211], v161 offset:34816
	ds_read_b128 v[212:215], v161 offset:35840
	ds_read_b128 v[216:219], v161 offset:36864
	ds_read_b128 v[220:223], v161 offset:37888
	ds_read_b128 v[224:227], v161 offset:38912
	ds_read_b128 v[228:231], v161 offset:39936
	global_load_lds_dwordx4 v[236:237], off
	v_lshl_add_u64 v[236:237], s[30:31], 0, v[134:135]
	s_mov_b32 m0, s45
	s_nop 0
	global_load_lds_dwordx4 v[236:237], off
	s_waitcnt vmcnt(8)
	s_waitcnt lgkmcnt(0)
	s_barrier
	s_waitcnt lgkmcnt(0)
	v_mfma_f32_16x16x32_bf16 v[126:129], v[164:167], v[200:203], v[126:129]
	v_mfma_f32_16x16x32_bf16 v[126:129], v[168:171], v[204:207], v[126:129]
	v_mfma_f32_16x16x32_bf16 v[118:121], v[164:167], v[208:211], v[118:121]
	v_mfma_f32_16x16x32_bf16 v[118:121], v[168:171], v[212:215], v[118:121]
	v_mfma_f32_16x16x32_bf16 v[102:105], v[164:167], v[216:219], v[102:105]
	v_mfma_f32_16x16x32_bf16 v[102:105], v[168:171], v[220:223], v[102:105]
	v_mfma_f32_16x16x32_bf16 v[86:89], v[164:167], v[224:227], v[86:89]
	v_mfma_f32_16x16x32_bf16 v[86:89], v[168:171], v[228:231], v[86:89]
	v_mfma_f32_16x16x32_bf16 v[122:125], v[172:175], v[200:203], v[122:125]
	v_mfma_f32_16x16x32_bf16 v[122:125], v[176:179], v[204:207], v[122:125]
	v_mfma_f32_16x16x32_bf16 v[110:113], v[172:175], v[208:211], v[110:113]
	v_mfma_f32_16x16x32_bf16 v[110:113], v[176:179], v[212:215], v[110:113]
	v_mfma_f32_16x16x32_bf16 v[94:97], v[172:175], v[216:219], v[94:97]
	v_mfma_f32_16x16x32_bf16 v[94:97], v[176:179], v[220:223], v[94:97]
	v_mfma_f32_16x16x32_bf16 v[78:81], v[172:175], v[224:227], v[78:81]
	v_mfma_f32_16x16x32_bf16 v[78:81], v[176:179], v[228:231], v[78:81]
	v_mfma_f32_16x16x32_bf16 v[114:117], v[184:187], v[200:203], v[114:117]
	v_mfma_f32_16x16x32_bf16 v[114:117], v[188:191], v[204:207], v[114:117]
	v_mfma_f32_16x16x32_bf16 v[98:101], v[184:187], v[208:211], v[98:101]
	v_mfma_f32_16x16x32_bf16 v[98:101], v[188:191], v[212:215], v[98:101]
	v_mfma_f32_16x16x32_bf16 v[82:85], v[184:187], v[216:219], v[82:85]
	v_mfma_f32_16x16x32_bf16 v[82:85], v[188:191], v[220:223], v[82:85]
	v_mfma_f32_16x16x32_bf16 v[70:73], v[184:187], v[224:227], v[70:73]
	v_mfma_f32_16x16x32_bf16 v[70:73], v[188:191], v[228:231], v[70:73]
	v_mfma_f32_16x16x32_bf16 v[106:109], v[192:195], v[200:203], v[106:109]
	v_mfma_f32_16x16x32_bf16 v[106:109], v[196:199], v[204:207], v[106:109]
	v_mfma_f32_16x16x32_bf16 v[90:93], v[192:195], v[208:211], v[90:93]
	v_mfma_f32_16x16x32_bf16 v[90:93], v[196:199], v[212:215], v[90:93]
	v_mfma_f32_16x16x32_bf16 v[74:77], v[192:195], v[216:219], v[74:77]
	v_mfma_f32_16x16x32_bf16 v[74:77], v[196:199], v[220:223], v[74:77]
	v_mfma_f32_16x16x32_bf16 v[66:69], v[192:195], v[224:227], v[66:69]
	v_mfma_f32_16x16x32_bf16 v[66:69], v[196:199], v[228:231], v[66:69]
	s_barrier
	s_add_i32 s30, s81, s34
	v_lshl_add_u64 v[148:149], v[148:149], 0, s[12:13]
	s_mov_b32 m0, s30
	ds_read_b128 v[200:203], v161 offset:49152
	ds_read_b128 v[204:207], v161 offset:50176
	ds_read_b128 v[208:211], v161 offset:51200
	ds_read_b128 v[212:215], v161 offset:52224
	ds_read_b128 v[216:219], v161 offset:53248
	ds_read_b128 v[220:223], v161 offset:54272
	ds_read_b128 v[224:227], v161 offset:55296
	ds_read_b128 v[228:231], v161 offset:56320
	global_load_lds_dwordx4 v[148:149], off
	s_add_i32 m0, s30, 0x2000
	s_add_u32 s28, s28, 0x100080
	v_lshl_add_u64 v[148:149], v[180:181], 0, s[12:13]
	s_addc_u32 s29, s29, 0
	s_add_i32 s30, s82, s34
	global_load_lds_dwordx4 v[148:149], off
	v_lshl_add_u64 v[148:149], s[28:29], 0, v[132:133]
	s_mov_b32 m0, s30
	s_nop 0
	global_load_lds_dwordx4 v[148:149], off
	v_lshl_add_u64 v[148:149], s[28:29], 0, v[136:137]
	s_add_i32 m0, s30, 0x2000
	s_nop 0
	global_load_lds_dwordx4 v[148:149], off
	v_lshl_add_u64 v[148:149], v[232:233], 0, s[12:13]
	s_mov_b32 m0, s46
	s_nop 0
	global_load_lds_dwordx4 v[148:149], off
	v_lshl_add_u64 v[148:149], v[234:235], 0, s[12:13]
	s_mov_b32 m0, s47
	s_nop 0
	global_load_lds_dwordx4 v[148:149], off
	s_waitcnt vmcnt(8)
	s_waitcnt lgkmcnt(0)
	s_barrier
	s_waitcnt lgkmcnt(0)
	v_mfma_f32_16x16x32_bf16 v[62:65], v[164:167], v[200:203], v[62:65]
	v_mfma_f32_16x16x32_bf16 v[62:65], v[168:171], v[204:207], v[62:65]
	v_mfma_f32_16x16x32_bf16 v[54:57], v[164:167], v[208:211], v[54:57]
	v_mfma_f32_16x16x32_bf16 v[54:57], v[168:171], v[212:215], v[54:57]
	v_mfma_f32_16x16x32_bf16 v[38:41], v[164:167], v[216:219], v[38:41]
	v_mfma_f32_16x16x32_bf16 v[38:41], v[168:171], v[220:223], v[38:41]
	v_mfma_f32_16x16x32_bf16 v[22:25], v[164:167], v[224:227], v[22:25]
	v_mfma_f32_16x16x32_bf16 v[22:25], v[168:171], v[228:231], v[22:25]
	v_mfma_f32_16x16x32_bf16 v[58:61], v[172:175], v[200:203], v[58:61]
	v_mfma_f32_16x16x32_bf16 v[58:61], v[176:179], v[204:207], v[58:61]
	v_mfma_f32_16x16x32_bf16 v[46:49], v[172:175], v[208:211], v[46:49]
	v_mfma_f32_16x16x32_bf16 v[46:49], v[176:179], v[212:215], v[46:49]
	v_mfma_f32_16x16x32_bf16 v[30:33], v[172:175], v[216:219], v[30:33]
	v_mfma_f32_16x16x32_bf16 v[30:33], v[176:179], v[220:223], v[30:33]
	v_mfma_f32_16x16x32_bf16 v[14:17], v[172:175], v[224:227], v[14:17]
	v_mfma_f32_16x16x32_bf16 v[14:17], v[176:179], v[228:231], v[14:17]
	v_mfma_f32_16x16x32_bf16 v[50:53], v[184:187], v[200:203], v[50:53]
	v_mfma_f32_16x16x32_bf16 v[50:53], v[188:191], v[204:207], v[50:53]
	v_mfma_f32_16x16x32_bf16 v[34:37], v[184:187], v[208:211], v[34:37]
	v_mfma_f32_16x16x32_bf16 v[34:37], v[188:191], v[212:215], v[34:37]
	v_mfma_f32_16x16x32_bf16 v[18:21], v[184:187], v[216:219], v[18:21]
	v_mfma_f32_16x16x32_bf16 v[18:21], v[188:191], v[220:223], v[18:21]
	v_mfma_f32_16x16x32_bf16 v[6:9], v[184:187], v[224:227], v[6:9]
	v_mfma_f32_16x16x32_bf16 v[6:9], v[188:191], v[228:231], v[6:9]
	v_mfma_f32_16x16x32_bf16 v[42:45], v[192:195], v[200:203], v[42:45]
	v_mfma_f32_16x16x32_bf16 v[42:45], v[196:199], v[204:207], v[42:45]
	v_mfma_f32_16x16x32_bf16 v[26:29], v[192:195], v[208:211], v[26:29]
	v_mfma_f32_16x16x32_bf16 v[26:29], v[196:199], v[212:215], v[26:29]
	v_mfma_f32_16x16x32_bf16 v[10:13], v[192:195], v[216:219], v[10:13]
	v_mfma_f32_16x16x32_bf16 v[10:13], v[196:199], v[220:223], v[10:13]
	v_mfma_f32_16x16x32_bf16 v[2:5], v[192:195], v[224:227], v[2:5]
	v_mfma_f32_16x16x32_bf16 v[2:5], v[196:199], v[228:231], v[2:5]
	s_barrier
	s_add_i32 s80, s80, 2
	s_add_u32 s26, s26, 0x100
	s_addc_u32 s27, s27, 0
	s_add_u32 s62, s62, 0x100
	s_addc_u32 s63, s63, 0
	s_cmp_gt_u32 s80, 61
	s_cbranch_scc0 .LBB0_177
	s_and_b64 vcc, exec, s[14:15]
	s_cbranch_vccz .LBB0_180
	s_barrier

.LBB0_197:
	ds_read_b128 v[164:167], v153
	ds_read_b128 v[168:171], v153 offset:1024
	ds_read_b128 v[172:175], v153 offset:2048
	ds_read_b128 v[176:179], v153 offset:3072
	ds_read_b128 v[184:187], v160
	ds_read_b128 v[188:191], v160 offset:1024
	ds_read_b128 v[192:195], v160 offset:2048
	ds_read_b128 v[196:199], v160 offset:3072
	s_add_u32 s30, s28, 0xfff00080
	s_addc_u32 s31, s29, -1
	s_cmp_eq_u32 s83, 60
	s_cselect_b32 s35, s21, s31
	s_cselect_b32 s34, s63, s30
	s_cselect_b32 s31, s19, s82
	s_cselect_b32 s30, s80, s81
	v_lshl_add_u64 v[148:149], s[28:29], 0, v[140:141]
	s_add_i32 m0, s27, 0xc000
	ds_read_b128 v[200:203], v161
	ds_read_b128 v[204:207], v161 offset:1024
	ds_read_b128 v[208:211], v161 offset:2048
	ds_read_b128 v[212:215], v161 offset:3072
	ds_read_b128 v[216:219], v161 offset:4096
	ds_read_b128 v[220:223], v161 offset:5120
	ds_read_b128 v[224:227], v161 offset:6144
	ds_read_b128 v[228:231], v161 offset:7168
	global_load_lds_dwordx4 v[148:149], off
	v_lshl_add_u64 v[148:149], s[28:29], 0, v[142:143]
	s_add_i32 m0, s27, 0xe000
	s_nop 0
	global_load_lds_dwordx4 v[148:149], off
	s_waitcnt vmcnt(8)
	s_waitcnt lgkmcnt(0)
	s_barrier
	s_waitcnt lgkmcnt(0)
	v_mfma_f32_16x16x32_bf16 v[126:129], v[164:167], v[200:203], v[126:129]
	v_mfma_f32_16x16x32_bf16 v[126:129], v[168:171], v[204:207], v[126:129]
	v_mfma_f32_16x16x32_bf16 v[110:113], v[164:167], v[208:211], v[110:113]
	v_mfma_f32_16x16x32_bf16 v[110:113], v[168:171], v[212:215], v[110:113]
	v_mfma_f32_16x16x32_bf16 v[94:97], v[164:167], v[216:219], v[94:97]
	v_mfma_f32_16x16x32_bf16 v[94:97], v[168:171], v[220:223], v[94:97]
	v_mfma_f32_16x16x32_bf16 v[78:81], v[164:167], v[224:227], v[78:81]
	v_mfma_f32_16x16x32_bf16 v[78:81], v[168:171], v[228:231], v[78:81]
	v_mfma_f32_16x16x32_bf16 v[122:125], v[172:175], v[200:203], v[122:125]
	v_mfma_f32_16x16x32_bf16 v[122:125], v[176:179], v[204:207], v[122:125]
	v_mfma_f32_16x16x32_bf16 v[106:109], v[172:175], v[208:211], v[106:109]
	v_mfma_f32_16x16x32_bf16 v[106:109], v[176:179], v[212:215], v[106:109]
	v_mfma_f32_16x16x32_bf16 v[90:93], v[172:175], v[216:219], v[90:93]
	v_mfma_f32_16x16x32_bf16 v[90:93], v[176:179], v[220:223], v[90:93]
	v_mfma_f32_16x16x32_bf16 v[74:77], v[172:175], v[224:227], v[74:77]
	v_mfma_f32_16x16x32_bf16 v[74:77], v[176:179], v[228:231], v[74:77]
	v_mfma_f32_16x16x32_bf16 v[118:121], v[184:187], v[200:203], v[118:121]
	v_mfma_f32_16x16x32_bf16 v[118:121], v[188:191], v[204:207], v[118:121]
	v_mfma_f32_16x16x32_bf16 v[102:105], v[184:187], v[208:211], v[102:105]
	v_mfma_f32_16x16x32_bf16 v[102:105], v[188:191], v[212:215], v[102:105]
	v_mfma_f32_16x16x32_bf16 v[86:89], v[184:187], v[216:219], v[86:89]
	v_mfma_f32_16x16x32_bf16 v[86:89], v[188:191], v[220:223], v[86:89]
	v_mfma_f32_16x16x32_bf16 v[70:73], v[184:187], v[224:227], v[70:73]
	v_mfma_f32_16x16x32_bf16 v[70:73], v[188:191], v[228:231], v[70:73]
	v_mfma_f32_16x16x32_bf16 v[114:117], v[192:195], v[200:203], v[114:117]
	v_mfma_f32_16x16x32_bf16 v[114:117], v[196:199], v[204:207], v[114:117]
	v_mfma_f32_16x16x32_bf16 v[98:101], v[192:195], v[208:211], v[98:101]
	v_mfma_f32_16x16x32_bf16 v[98:101], v[196:199], v[212:215], v[98:101]
	v_mfma_f32_16x16x32_bf16 v[82:85], v[192:195], v[216:219], v[82:85]
	v_mfma_f32_16x16x32_bf16 v[82:85], v[196:199], v[220:223], v[82:85]
	v_mfma_f32_16x16x32_bf16 v[66:69], v[192:195], v[224:227], v[66:69]
	v_mfma_f32_16x16x32_bf16 v[66:69], v[196:199], v[228:231], v[66:69]
	s_barrier
	s_add_i32 s84, s58, s43
	v_lshl_add_u64 v[148:149], s[30:31], 0, v[132:133]
	s_mov_b32 m0, s84
	ds_read_b128 v[200:203], v161 offset:16384
	ds_read_b128 v[204:207], v161 offset:17408
	ds_read_b128 v[208:211], v161 offset:18432
	ds_read_b128 v[212:215], v161 offset:19456
	ds_read_b128 v[216:219], v161 offset:20480
	ds_read_b128 v[220:223], v161 offset:21504
	ds_read_b128 v[224:227], v161 offset:22528
	ds_read_b128 v[228:231], v161 offset:23552
	global_load_lds_dwordx4 v[148:149], off
	s_add_i32 m0, s84, 0x2000
	s_add_u32 s84, s30, 0x100000
	v_lshl_add_u64 v[180:181], s[30:31], 0, v[136:137]
	s_addc_u32 s85, s31, 0
	s_add_i32 s86, s59, s43
	global_load_lds_dwordx4 v[180:181], off
	v_lshl_add_u64 v[232:233], s[84:85], 0, v[132:133]
	s_mov_b32 m0, s86
	v_lshl_add_u64 v[234:235], s[34:35], 0, v[134:135]
	global_load_lds_dwordx4 v[232:233], off
	v_lshl_add_u64 v[232:233], s[84:85], 0, v[136:137]
	s_add_i32 m0, s86, 0x2000
	s_nop 0
	global_load_lds_dwordx4 v[232:233], off
	v_lshl_add_u64 v[232:233], s[34:35], 0, v[130:131]
	s_mov_b32 m0, s27
	s_nop 0
	global_load_lds_dwordx4 v[232:233], off
	s_mov_b32 m0, s46
	s_nop 0
	global_load_lds_dwordx4 v[234:235], off
	s_waitcnt vmcnt(8)
	s_waitcnt lgkmcnt(0)
	s_barrier
	s_waitcnt lgkmcnt(0)
	v_mfma_f32_16x16x32_bf16 v[62:65], v[164:167], v[200:203], v[62:65]
	v_mfma_f32_16x16x32_bf16 v[62:65], v[168:171], v[204:207], v[62:65]
	v_mfma_f32_16x16x32_bf16 v[46:49], v[164:167], v[208:211], v[46:49]
	v_mfma_f32_16x16x32_bf16 v[46:49], v[168:171], v[212:215], v[46:49]
	v_mfma_f32_16x16x32_bf16 v[30:33], v[164:167], v[216:219], v[30:33]
	v_mfma_f32_16x16x32_bf16 v[30:33], v[168:171], v[220:223], v[30:33]
	v_mfma_f32_16x16x32_bf16 v[14:17], v[164:167], v[224:227], v[14:17]
	v_mfma_f32_16x16x32_bf16 v[14:17], v[168:171], v[228:231], v[14:17]
	v_mfma_f32_16x16x32_bf16 v[58:61], v[172:175], v[200:203], v[58:61]
	v_mfma_f32_16x16x32_bf16 v[58:61], v[176:179], v[204:207], v[58:61]
	v_mfma_f32_16x16x32_bf16 v[42:45], v[172:175], v[208:211], v[42:45]
	v_mfma_f32_16x16x32_bf16 v[42:45], v[176:179], v[212:215], v[42:45]
	v_mfma_f32_16x16x32_bf16 v[26:29], v[172:175], v[216:219], v[26:29]
	v_mfma_f32_16x16x32_bf16 v[26:29], v[176:179], v[220:223], v[26:29]
	v_mfma_f32_16x16x32_bf16 v[10:13], v[172:175], v[224:227], v[10:13]
	v_mfma_f32_16x16x32_bf16 v[10:13], v[176:179], v[228:231], v[10:13]
	v_mfma_f32_16x16x32_bf16 v[54:57], v[184:187], v[200:203], v[54:57]
	v_mfma_f32_16x16x32_bf16 v[54:57], v[188:191], v[204:207], v[54:57]
	v_mfma_f32_16x16x32_bf16 v[38:41], v[184:187], v[208:211], v[38:41]
	v_mfma_f32_16x16x32_bf16 v[38:41], v[188:191], v[212:215], v[38:41]
	v_mfma_f32_16x16x32_bf16 v[22:25], v[184:187], v[216:219], v[22:25]
	v_mfma_f32_16x16x32_bf16 v[22:25], v[188:191], v[220:223], v[22:25]
	v_mfma_f32_16x16x32_bf16 v[6:9], v[184:187], v[224:227], v[6:9]
	v_mfma_f32_16x16x32_bf16 v[6:9], v[188:191], v[228:231], v[6:9]
	v_mfma_f32_16x16x32_bf16 v[50:53], v[192:195], v[200:203], v[50:53]
	v_mfma_f32_16x16x32_bf16 v[50:53], v[196:199], v[204:207], v[50:53]
	v_mfma_f32_16x16x32_bf16 v[34:37], v[192:195], v[208:211], v[34:37]
	v_mfma_f32_16x16x32_bf16 v[34:37], v[196:199], v[212:215], v[34:37]
	v_mfma_f32_16x16x32_bf16 v[18:21], v[192:195], v[216:219], v[18:21]
	v_mfma_f32_16x16x32_bf16 v[18:21], v[196:199], v[220:223], v[18:21]
	v_mfma_f32_16x16x32_bf16 v[2:5], v[192:195], v[224:227], v[2:5]
	v_mfma_f32_16x16x32_bf16 v[2:5], v[196:199], v[228:231], v[2:5]
	s_barrier
	s_add_i32 s84, 0, 0x18000
	v_add_u32_e32 v162, s84, v151
	s_add_i32 s85, 0, 0x1c000
	ds_read_b128 v[164:167], v162
	ds_read_b128 v[168:171], v162 offset:1024
	ds_read_b128 v[172:175], v162 offset:2048
	ds_read_b128 v[176:179], v162 offset:3072
	v_add_u32_e32 v162, s85, v151
	ds_read_b128 v[184:187], v162
	ds_read_b128 v[188:191], v162 offset:1024
	ds_read_b128 v[192:195], v162 offset:2048
	ds_read_b128 v[196:199], v162 offset:3072
	s_add_u32 s34, s34, 0x100000
	s_addc_u32 s35, s35, 0
	s_mov_b32 m0, s47
	v_lshl_add_u64 v[236:237], s[34:35], 0, v[130:131]
	ds_read_b128 v[200:203], v161 offset:32768
	ds_read_b128 v[204:207], v161 offset:33792
	ds_read_b128 v[208:211], v161 offset:34816
	ds_read_b128 v[212:215], v161 offset:35840
	ds_read_b128 v[216:219], v161 offset:36864
	ds_read_b128 v[220:223], v161 offset:37888
	ds_read_b128 v[224:227], v161 offset:38912
	ds_read_b128 v[228:231], v161 offset:39936
	global_load_lds_dwordx4 v[236:237], off
	v_lshl_add_u64 v[236:237], s[34:35], 0, v[134:135]
	s_mov_b32 m0, s50
	s_nop 0
	global_load_lds_dwordx4 v[236:237], off
	s_waitcnt vmcnt(8)
	s_waitcnt lgkmcnt(0)
	s_barrier
	s_waitcnt lgkmcnt(0)
	v_mfma_f32_16x16x32_bf16 v[126:129], v[164:167], v[200:203], v[126:129]
	v_mfma_f32_16x16x32_bf16 v[126:129], v[168:171], v[204:207], v[126:129]
	v_mfma_f32_16x16x32_bf16 v[110:113], v[164:167], v[208:211], v[110:113]
	v_mfma_f32_16x16x32_bf16 v[110:113], v[168:171], v[212:215], v[110:113]
	v_mfma_f32_16x16x32_bf16 v[94:97], v[164:167], v[216:219], v[94:97]
	v_mfma_f32_16x16x32_bf16 v[94:97], v[168:171], v[220:223], v[94:97]
	v_mfma_f32_16x16x32_bf16 v[78:81], v[164:167], v[224:227], v[78:81]
	v_mfma_f32_16x16x32_bf16 v[78:81], v[168:171], v[228:231], v[78:81]
	v_mfma_f32_16x16x32_bf16 v[122:125], v[172:175], v[200:203], v[122:125]
	v_mfma_f32_16x16x32_bf16 v[122:125], v[176:179], v[204:207], v[122:125]
	v_mfma_f32_16x16x32_bf16 v[106:109], v[172:175], v[208:211], v[106:109]
	v_mfma_f32_16x16x32_bf16 v[106:109], v[176:179], v[212:215], v[106:109]
	v_mfma_f32_16x16x32_bf16 v[90:93], v[172:175], v[216:219], v[90:93]
	v_mfma_f32_16x16x32_bf16 v[90:93], v[176:179], v[220:223], v[90:93]
	v_mfma_f32_16x16x32_bf16 v[74:77], v[172:175], v[224:227], v[74:77]
	v_mfma_f32_16x16x32_bf16 v[74:77], v[176:179], v[228:231], v[74:77]
	v_mfma_f32_16x16x32_bf16 v[118:121], v[184:187], v[200:203], v[118:121]
	v_mfma_f32_16x16x32_bf16 v[118:121], v[188:191], v[204:207], v[118:121]
	v_mfma_f32_16x16x32_bf16 v[102:105], v[184:187], v[208:211], v[102:105]
	v_mfma_f32_16x16x32_bf16 v[102:105], v[188:191], v[212:215], v[102:105]
	v_mfma_f32_16x16x32_bf16 v[86:89], v[184:187], v[216:219], v[86:89]
	v_mfma_f32_16x16x32_bf16 v[86:89], v[188:191], v[220:223], v[86:89]
	v_mfma_f32_16x16x32_bf16 v[70:73], v[184:187], v[224:227], v[70:73]
	v_mfma_f32_16x16x32_bf16 v[70:73], v[188:191], v[228:231], v[70:73]
	v_mfma_f32_16x16x32_bf16 v[114:117], v[192:195], v[200:203], v[114:117]
	v_mfma_f32_16x16x32_bf16 v[114:117], v[196:199], v[204:207], v[114:117]
	v_mfma_f32_16x16x32_bf16 v[98:101], v[192:195], v[208:211], v[98:101]
	v_mfma_f32_16x16x32_bf16 v[98:101], v[196:199], v[212:215], v[98:101]
	v_mfma_f32_16x16x32_bf16 v[82:85], v[192:195], v[216:219], v[82:85]
	v_mfma_f32_16x16x32_bf16 v[82:85], v[196:199], v[220:223], v[82:85]
	v_mfma_f32_16x16x32_bf16 v[66:69], v[192:195], v[224:227], v[66:69]
	v_mfma_f32_16x16x32_bf16 v[66:69], v[196:199], v[228:231], v[66:69]
	s_barrier
	s_add_i32 s34, s84, s43
	v_lshl_add_u64 v[148:149], v[148:149], 0, s[14:15]
	s_mov_b32 m0, s34
	ds_read_b128 v[200:203], v161 offset:49152
	ds_read_b128 v[204:207], v161 offset:50176
	ds_read_b128 v[208:211], v161 offset:51200
	ds_read_b128 v[212:215], v161 offset:52224
	ds_read_b128 v[216:219], v161 offset:53248
	ds_read_b128 v[220:223], v161 offset:54272
	ds_read_b128 v[224:227], v161 offset:55296
	ds_read_b128 v[228:231], v161 offset:56320
	global_load_lds_dwordx4 v[148:149], off
	s_add_i32 m0, s34, 0x2000
	s_add_u32 s30, s30, 0x100080
	v_lshl_add_u64 v[148:149], v[180:181], 0, s[14:15]
	s_addc_u32 s31, s31, 0
	s_add_i32 s34, s85, s43
	global_load_lds_dwordx4 v[148:149], off
	v_lshl_add_u64 v[148:149], s[30:31], 0, v[132:133]
	s_mov_b32 m0, s34
	s_nop 0
	global_load_lds_dwordx4 v[148:149], off
	v_lshl_add_u64 v[148:149], s[30:31], 0, v[136:137]
	s_add_i32 m0, s34, 0x2000
	s_nop 0
	global_load_lds_dwordx4 v[148:149], off
	v_lshl_add_u64 v[148:149], v[232:233], 0, s[14:15]
	s_mov_b32 m0, s52
	s_nop 0
	global_load_lds_dwordx4 v[148:149], off
	v_lshl_add_u64 v[148:149], v[234:235], 0, s[14:15]
	s_mov_b32 m0, s53
	s_nop 0
	global_load_lds_dwordx4 v[148:149], off
	s_waitcnt vmcnt(8)
	s_waitcnt lgkmcnt(0)
	s_barrier
	s_waitcnt lgkmcnt(0)
	v_mfma_f32_16x16x32_bf16 v[62:65], v[164:167], v[200:203], v[62:65]
	v_mfma_f32_16x16x32_bf16 v[62:65], v[168:171], v[204:207], v[62:65]
	v_mfma_f32_16x16x32_bf16 v[46:49], v[164:167], v[208:211], v[46:49]
	v_mfma_f32_16x16x32_bf16 v[46:49], v[168:171], v[212:215], v[46:49]
	v_mfma_f32_16x16x32_bf16 v[30:33], v[164:167], v[216:219], v[30:33]
	v_mfma_f32_16x16x32_bf16 v[30:33], v[168:171], v[220:223], v[30:33]
	v_mfma_f32_16x16x32_bf16 v[14:17], v[164:167], v[224:227], v[14:17]
	v_mfma_f32_16x16x32_bf16 v[14:17], v[168:171], v[228:231], v[14:17]
	v_mfma_f32_16x16x32_bf16 v[58:61], v[172:175], v[200:203], v[58:61]
	v_mfma_f32_16x16x32_bf16 v[58:61], v[176:179], v[204:207], v[58:61]
	v_mfma_f32_16x16x32_bf16 v[42:45], v[172:175], v[208:211], v[42:45]
	v_mfma_f32_16x16x32_bf16 v[42:45], v[176:179], v[212:215], v[42:45]
	v_mfma_f32_16x16x32_bf16 v[26:29], v[172:175], v[216:219], v[26:29]
	v_mfma_f32_16x16x32_bf16 v[26:29], v[176:179], v[220:223], v[26:29]
	v_mfma_f32_16x16x32_bf16 v[10:13], v[172:175], v[224:227], v[10:13]
	v_mfma_f32_16x16x32_bf16 v[10:13], v[176:179], v[228:231], v[10:13]
	v_mfma_f32_16x16x32_bf16 v[54:57], v[184:187], v[200:203], v[54:57]
	v_mfma_f32_16x16x32_bf16 v[54:57], v[188:191], v[204:207], v[54:57]
	v_mfma_f32_16x16x32_bf16 v[38:41], v[184:187], v[208:211], v[38:41]
	v_mfma_f32_16x16x32_bf16 v[38:41], v[188:191], v[212:215], v[38:41]
	v_mfma_f32_16x16x32_bf16 v[22:25], v[184:187], v[216:219], v[22:25]
	v_mfma_f32_16x16x32_bf16 v[22:25], v[188:191], v[220:223], v[22:25]
	v_mfma_f32_16x16x32_bf16 v[6:9], v[184:187], v[224:227], v[6:9]
	v_mfma_f32_16x16x32_bf16 v[6:9], v[188:191], v[228:231], v[6:9]
	v_mfma_f32_16x16x32_bf16 v[50:53], v[192:195], v[200:203], v[50:53]
	v_mfma_f32_16x16x32_bf16 v[50:53], v[196:199], v[204:207], v[50:53]
	v_mfma_f32_16x16x32_bf16 v[34:37], v[192:195], v[208:211], v[34:37]
	v_mfma_f32_16x16x32_bf16 v[34:37], v[196:199], v[212:215], v[34:37]
	v_mfma_f32_16x16x32_bf16 v[18:21], v[192:195], v[216:219], v[18:21]
	v_mfma_f32_16x16x32_bf16 v[18:21], v[196:199], v[220:223], v[18:21]
	v_mfma_f32_16x16x32_bf16 v[2:5], v[192:195], v[224:227], v[2:5]
	v_mfma_f32_16x16x32_bf16 v[2:5], v[196:199], v[228:231], v[2:5]
	s_barrier
	s_add_i32 s83, s83, 2
	s_add_u32 s28, s28, 0x100
	s_addc_u32 s29, s29, 0
	s_add_u32 s81, s81, 0x100
	s_addc_u32 s82, s82, 0
	s_cmp_gt_u32 s83, 61
	s_cbranch_scc0 .LBB0_197
	s_and_b64 vcc, exec, s[16:17]
	s_cbranch_vccz .LBB0_200
	s_barrier

.LBB0_217:
	ds_read_b128 v[164:167], v153
	ds_read_b128 v[168:171], v153 offset:1024
	ds_read_b128 v[172:175], v153 offset:2048
	ds_read_b128 v[176:179], v153 offset:3072
	ds_read_b128 v[184:187], v160
	ds_read_b128 v[188:191], v160 offset:1024
	ds_read_b128 v[192:195], v160 offset:2048
	ds_read_b128 v[196:199], v160 offset:3072
	s_add_u32 s30, s28, 0xfff00080
	s_addc_u32 s31, s29, -1
	s_cmp_eq_u32 s83, 60
	s_cselect_b32 s35, s21, s31
	s_cselect_b32 s34, s63, s30
	s_cselect_b32 s31, s19, s82
	s_cselect_b32 s30, s80, s81
	v_lshl_add_u64 v[148:149], s[28:29], 0, v[140:141]
	s_add_i32 m0, s27, 0xc000
	ds_read_b128 v[200:203], v161
	ds_read_b128 v[204:207], v161 offset:1024
	ds_read_b128 v[208:211], v161 offset:2048
	ds_read_b128 v[212:215], v161 offset:3072
	ds_read_b128 v[216:219], v161 offset:4096
	ds_read_b128 v[220:223], v161 offset:5120
	ds_read_b128 v[224:227], v161 offset:6144
	ds_read_b128 v[228:231], v161 offset:7168
	global_load_lds_dwordx4 v[148:149], off
	v_lshl_add_u64 v[148:149], s[28:29], 0, v[142:143]
	s_add_i32 m0, s27, 0xe000
	s_nop 0
	global_load_lds_dwordx4 v[148:149], off
	s_waitcnt vmcnt(8)
	s_waitcnt lgkmcnt(0)
	s_barrier
	s_waitcnt lgkmcnt(0)
	v_mfma_f32_16x16x32_bf16 v[126:129], v[164:167], v[200:203], v[126:129]
	v_mfma_f32_16x16x32_bf16 v[126:129], v[168:171], v[204:207], v[126:129]
	v_mfma_f32_16x16x32_bf16 v[118:121], v[164:167], v[208:211], v[118:121]
	v_mfma_f32_16x16x32_bf16 v[118:121], v[168:171], v[212:215], v[118:121]
	v_mfma_f32_16x16x32_bf16 v[102:105], v[164:167], v[216:219], v[102:105]
	v_mfma_f32_16x16x32_bf16 v[102:105], v[168:171], v[220:223], v[102:105]
	v_mfma_f32_16x16x32_bf16 v[86:89], v[164:167], v[224:227], v[86:89]
	v_mfma_f32_16x16x32_bf16 v[86:89], v[168:171], v[228:231], v[86:89]
	v_mfma_f32_16x16x32_bf16 v[122:125], v[172:175], v[200:203], v[122:125]
	v_mfma_f32_16x16x32_bf16 v[122:125], v[176:179], v[204:207], v[122:125]
	v_mfma_f32_16x16x32_bf16 v[110:113], v[172:175], v[208:211], v[110:113]
	v_mfma_f32_16x16x32_bf16 v[110:113], v[176:179], v[212:215], v[110:113]
	v_mfma_f32_16x16x32_bf16 v[94:97], v[172:175], v[216:219], v[94:97]
	v_mfma_f32_16x16x32_bf16 v[94:97], v[176:179], v[220:223], v[94:97]
	v_mfma_f32_16x16x32_bf16 v[78:81], v[172:175], v[224:227], v[78:81]
	v_mfma_f32_16x16x32_bf16 v[78:81], v[176:179], v[228:231], v[78:81]
	v_mfma_f32_16x16x32_bf16 v[114:117], v[184:187], v[200:203], v[114:117]
	v_mfma_f32_16x16x32_bf16 v[114:117], v[188:191], v[204:207], v[114:117]
	v_mfma_f32_16x16x32_bf16 v[98:101], v[184:187], v[208:211], v[98:101]
	v_mfma_f32_16x16x32_bf16 v[98:101], v[188:191], v[212:215], v[98:101]
	v_mfma_f32_16x16x32_bf16 v[82:85], v[184:187], v[216:219], v[82:85]
	v_mfma_f32_16x16x32_bf16 v[82:85], v[188:191], v[220:223], v[82:85]
	v_mfma_f32_16x16x32_bf16 v[70:73], v[184:187], v[224:227], v[70:73]
	v_mfma_f32_16x16x32_bf16 v[70:73], v[188:191], v[228:231], v[70:73]
	v_mfma_f32_16x16x32_bf16 v[106:109], v[192:195], v[200:203], v[106:109]
	v_mfma_f32_16x16x32_bf16 v[106:109], v[196:199], v[204:207], v[106:109]
	v_mfma_f32_16x16x32_bf16 v[90:93], v[192:195], v[208:211], v[90:93]
	v_mfma_f32_16x16x32_bf16 v[90:93], v[196:199], v[212:215], v[90:93]
	v_mfma_f32_16x16x32_bf16 v[74:77], v[192:195], v[216:219], v[74:77]
	v_mfma_f32_16x16x32_bf16 v[74:77], v[196:199], v[220:223], v[74:77]
	v_mfma_f32_16x16x32_bf16 v[66:69], v[192:195], v[224:227], v[66:69]
	v_mfma_f32_16x16x32_bf16 v[66:69], v[196:199], v[228:231], v[66:69]
	s_barrier
	s_add_i32 s84, s58, s43
	v_lshl_add_u64 v[148:149], s[30:31], 0, v[132:133]
	s_mov_b32 m0, s84
	ds_read_b128 v[200:203], v161 offset:16384
	ds_read_b128 v[204:207], v161 offset:17408
	ds_read_b128 v[208:211], v161 offset:18432
	ds_read_b128 v[212:215], v161 offset:19456
	ds_read_b128 v[216:219], v161 offset:20480
	ds_read_b128 v[220:223], v161 offset:21504
	ds_read_b128 v[224:227], v161 offset:22528
	ds_read_b128 v[228:231], v161 offset:23552
	global_load_lds_dwordx4 v[148:149], off
	s_add_i32 m0, s84, 0x2000
	s_add_u32 s84, s30, 0x100000
	v_lshl_add_u64 v[180:181], s[30:31], 0, v[136:137]
	s_addc_u32 s85, s31, 0
	s_add_i32 s86, s59, s43
	global_load_lds_dwordx4 v[180:181], off
	v_lshl_add_u64 v[232:233], s[84:85], 0, v[132:133]
	s_mov_b32 m0, s86
	v_lshl_add_u64 v[234:235], s[34:35], 0, v[134:135]
	global_load_lds_dwordx4 v[232:233], off
	v_lshl_add_u64 v[232:233], s[84:85], 0, v[136:137]
	s_add_i32 m0, s86, 0x2000
	s_nop 0
	global_load_lds_dwordx4 v[232:233], off
	v_lshl_add_u64 v[232:233], s[34:35], 0, v[130:131]
	s_mov_b32 m0, s27
	s_nop 0
	global_load_lds_dwordx4 v[232:233], off
	s_mov_b32 m0, s46
	s_nop 0
	global_load_lds_dwordx4 v[234:235], off
	s_waitcnt vmcnt(8)
	s_waitcnt lgkmcnt(0)
	s_barrier
	s_waitcnt lgkmcnt(0)
	v_mfma_f32_16x16x32_bf16 v[62:65], v[164:167], v[200:203], v[62:65]
	v_mfma_f32_16x16x32_bf16 v[62:65], v[168:171], v[204:207], v[62:65]
	v_mfma_f32_16x16x32_bf16 v[54:57], v[164:167], v[208:211], v[54:57]
	v_mfma_f32_16x16x32_bf16 v[54:57], v[168:171], v[212:215], v[54:57]
	v_mfma_f32_16x16x32_bf16 v[38:41], v[164:167], v[216:219], v[38:41]
	v_mfma_f32_16x16x32_bf16 v[38:41], v[168:171], v[220:223], v[38:41]
	v_mfma_f32_16x16x32_bf16 v[22:25], v[164:167], v[224:227], v[22:25]
	v_mfma_f32_16x16x32_bf16 v[22:25], v[168:171], v[228:231], v[22:25]
	v_mfma_f32_16x16x32_bf16 v[58:61], v[172:175], v[200:203], v[58:61]
	v_mfma_f32_16x16x32_bf16 v[58:61], v[176:179], v[204:207], v[58:61]
	v_mfma_f32_16x16x32_bf16 v[46:49], v[172:175], v[208:211], v[46:49]
	v_mfma_f32_16x16x32_bf16 v[46:49], v[176:179], v[212:215], v[46:49]
	v_mfma_f32_16x16x32_bf16 v[30:33], v[172:175], v[216:219], v[30:33]
	v_mfma_f32_16x16x32_bf16 v[30:33], v[176:179], v[220:223], v[30:33]
	v_mfma_f32_16x16x32_bf16 v[14:17], v[172:175], v[224:227], v[14:17]
	v_mfma_f32_16x16x32_bf16 v[14:17], v[176:179], v[228:231], v[14:17]
	v_mfma_f32_16x16x32_bf16 v[50:53], v[184:187], v[200:203], v[50:53]
	v_mfma_f32_16x16x32_bf16 v[50:53], v[188:191], v[204:207], v[50:53]
	v_mfma_f32_16x16x32_bf16 v[34:37], v[184:187], v[208:211], v[34:37]
	v_mfma_f32_16x16x32_bf16 v[34:37], v[188:191], v[212:215], v[34:37]
	v_mfma_f32_16x16x32_bf16 v[18:21], v[184:187], v[216:219], v[18:21]
	v_mfma_f32_16x16x32_bf16 v[18:21], v[188:191], v[220:223], v[18:21]
	v_mfma_f32_16x16x32_bf16 v[6:9], v[184:187], v[224:227], v[6:9]
	v_mfma_f32_16x16x32_bf16 v[6:9], v[188:191], v[228:231], v[6:9]
	v_mfma_f32_16x16x32_bf16 v[42:45], v[192:195], v[200:203], v[42:45]
	v_mfma_f32_16x16x32_bf16 v[42:45], v[196:199], v[204:207], v[42:45]
	v_mfma_f32_16x16x32_bf16 v[26:29], v[192:195], v[208:211], v[26:29]
	v_mfma_f32_16x16x32_bf16 v[26:29], v[196:199], v[212:215], v[26:29]
	v_mfma_f32_16x16x32_bf16 v[10:13], v[192:195], v[216:219], v[10:13]
	v_mfma_f32_16x16x32_bf16 v[10:13], v[196:199], v[220:223], v[10:13]
	v_mfma_f32_16x16x32_bf16 v[2:5], v[192:195], v[224:227], v[2:5]
	v_mfma_f32_16x16x32_bf16 v[2:5], v[196:199], v[228:231], v[2:5]
	s_barrier
	s_add_i32 s84, 0, 0x18000
	v_add_u32_e32 v162, s84, v151
	s_add_i32 s85, 0, 0x1c000
	ds_read_b128 v[164:167], v162
	ds_read_b128 v[168:171], v162 offset:1024
	ds_read_b128 v[172:175], v162 offset:2048
	ds_read_b128 v[176:179], v162 offset:3072
	v_add_u32_e32 v162, s85, v151
	ds_read_b128 v[184:187], v162
	ds_read_b128 v[188:191], v162 offset:1024
	ds_read_b128 v[192:195], v162 offset:2048
	ds_read_b128 v[196:199], v162 offset:3072
	s_add_u32 s34, s34, 0x100000
	s_addc_u32 s35, s35, 0
	s_mov_b32 m0, s47
	v_lshl_add_u64 v[236:237], s[34:35], 0, v[130:131]
	ds_read_b128 v[200:203], v161 offset:32768
	ds_read_b128 v[204:207], v161 offset:33792
	ds_read_b128 v[208:211], v161 offset:34816
	ds_read_b128 v[212:215], v161 offset:35840
	ds_read_b128 v[216:219], v161 offset:36864
	ds_read_b128 v[220:223], v161 offset:37888
	ds_read_b128 v[224:227], v161 offset:38912
	ds_read_b128 v[228:231], v161 offset:39936
	global_load_lds_dwordx4 v[236:237], off
	v_lshl_add_u64 v[236:237], s[34:35], 0, v[134:135]
	s_mov_b32 m0, s50
	s_nop 0
	global_load_lds_dwordx4 v[236:237], off
	s_waitcnt vmcnt(8)
	s_waitcnt lgkmcnt(0)
	s_barrier
	s_waitcnt lgkmcnt(0)
	v_mfma_f32_16x16x32_bf16 v[126:129], v[164:167], v[200:203], v[126:129]
	v_mfma_f32_16x16x32_bf16 v[126:129], v[168:171], v[204:207], v[126:129]
	v_mfma_f32_16x16x32_bf16 v[118:121], v[164:167], v[208:211], v[118:121]
	v_mfma_f32_16x16x32_bf16 v[118:121], v[168:171], v[212:215], v[118:121]
	v_mfma_f32_16x16x32_bf16 v[102:105], v[164:167], v[216:219], v[102:105]
	v_mfma_f32_16x16x32_bf16 v[102:105], v[168:171], v[220:223], v[102:105]
	v_mfma_f32_16x16x32_bf16 v[86:89], v[164:167], v[224:227], v[86:89]
	v_mfma_f32_16x16x32_bf16 v[86:89], v[168:171], v[228:231], v[86:89]
	v_mfma_f32_16x16x32_bf16 v[122:125], v[172:175], v[200:203], v[122:125]
	v_mfma_f32_16x16x32_bf16 v[122:125], v[176:179], v[204:207], v[122:125]
	v_mfma_f32_16x16x32_bf16 v[110:113], v[172:175], v[208:211], v[110:113]
	v_mfma_f32_16x16x32_bf16 v[110:113], v[176:179], v[212:215], v[110:113]
	v_mfma_f32_16x16x32_bf16 v[94:97], v[172:175], v[216:219], v[94:97]
	v_mfma_f32_16x16x32_bf16 v[94:97], v[176:179], v[220:223], v[94:97]
	v_mfma_f32_16x16x32_bf16 v[78:81], v[172:175], v[224:227], v[78:81]
	v_mfma_f32_16x16x32_bf16 v[78:81], v[176:179], v[228:231], v[78:81]
	v_mfma_f32_16x16x32_bf16 v[114:117], v[184:187], v[200:203], v[114:117]
	v_mfma_f32_16x16x32_bf16 v[114:117], v[188:191], v[204:207], v[114:117]
	v_mfma_f32_16x16x32_bf16 v[98:101], v[184:187], v[208:211], v[98:101]
	v_mfma_f32_16x16x32_bf16 v[98:101], v[188:191], v[212:215], v[98:101]
	v_mfma_f32_16x16x32_bf16 v[82:85], v[184:187], v[216:219], v[82:85]
	v_mfma_f32_16x16x32_bf16 v[82:85], v[188:191], v[220:223], v[82:85]
	v_mfma_f32_16x16x32_bf16 v[70:73], v[184:187], v[224:227], v[70:73]
	v_mfma_f32_16x16x32_bf16 v[70:73], v[188:191], v[228:231], v[70:73]
	v_mfma_f32_16x16x32_bf16 v[106:109], v[192:195], v[200:203], v[106:109]
	v_mfma_f32_16x16x32_bf16 v[106:109], v[196:199], v[204:207], v[106:109]
	v_mfma_f32_16x16x32_bf16 v[90:93], v[192:195], v[208:211], v[90:93]
	v_mfma_f32_16x16x32_bf16 v[90:93], v[196:199], v[212:215], v[90:93]
	v_mfma_f32_16x16x32_bf16 v[74:77], v[192:195], v[216:219], v[74:77]
	v_mfma_f32_16x16x32_bf16 v[74:77], v[196:199], v[220:223], v[74:77]
	v_mfma_f32_16x16x32_bf16 v[66:69], v[192:195], v[224:227], v[66:69]
	v_mfma_f32_16x16x32_bf16 v[66:69], v[196:199], v[228:231], v[66:69]
	s_barrier
	s_add_i32 s34, s84, s43
	v_lshl_add_u64 v[148:149], v[148:149], 0, s[14:15]
	s_mov_b32 m0, s34
	ds_read_b128 v[200:203], v161 offset:49152
	ds_read_b128 v[204:207], v161 offset:50176
	ds_read_b128 v[208:211], v161 offset:51200
	ds_read_b128 v[212:215], v161 offset:52224
	ds_read_b128 v[216:219], v161 offset:53248
	ds_read_b128 v[220:223], v161 offset:54272
	ds_read_b128 v[224:227], v161 offset:55296
	ds_read_b128 v[228:231], v161 offset:56320
	global_load_lds_dwordx4 v[148:149], off
	s_add_i32 m0, s34, 0x2000
	s_add_u32 s30, s30, 0x100080
	v_lshl_add_u64 v[148:149], v[180:181], 0, s[14:15]
	s_addc_u32 s31, s31, 0
	s_add_i32 s34, s85, s43
	global_load_lds_dwordx4 v[148:149], off
	v_lshl_add_u64 v[148:149], s[30:31], 0, v[132:133]
	s_mov_b32 m0, s34
	s_nop 0
	global_load_lds_dwordx4 v[148:149], off
	v_lshl_add_u64 v[148:149], s[30:31], 0, v[136:137]
	s_add_i32 m0, s34, 0x2000
	s_nop 0
	global_load_lds_dwordx4 v[148:149], off
	v_lshl_add_u64 v[148:149], v[232:233], 0, s[14:15]
	s_mov_b32 m0, s52
	s_nop 0
	global_load_lds_dwordx4 v[148:149], off
	v_lshl_add_u64 v[148:149], v[234:235], 0, s[14:15]
	s_mov_b32 m0, s53
	s_nop 0
	global_load_lds_dwordx4 v[148:149], off
	s_waitcnt vmcnt(8)
	s_waitcnt lgkmcnt(0)
	s_barrier
	s_waitcnt lgkmcnt(0)
	v_mfma_f32_16x16x32_bf16 v[62:65], v[164:167], v[200:203], v[62:65]
	v_mfma_f32_16x16x32_bf16 v[62:65], v[168:171], v[204:207], v[62:65]
	v_mfma_f32_16x16x32_bf16 v[54:57], v[164:167], v[208:211], v[54:57]
	v_mfma_f32_16x16x32_bf16 v[54:57], v[168:171], v[212:215], v[54:57]
	v_mfma_f32_16x16x32_bf16 v[38:41], v[164:167], v[216:219], v[38:41]
	v_mfma_f32_16x16x32_bf16 v[38:41], v[168:171], v[220:223], v[38:41]
	v_mfma_f32_16x16x32_bf16 v[22:25], v[164:167], v[224:227], v[22:25]
	v_mfma_f32_16x16x32_bf16 v[22:25], v[168:171], v[228:231], v[22:25]
	v_mfma_f32_16x16x32_bf16 v[58:61], v[172:175], v[200:203], v[58:61]
	v_mfma_f32_16x16x32_bf16 v[58:61], v[176:179], v[204:207], v[58:61]
	v_mfma_f32_16x16x32_bf16 v[46:49], v[172:175], v[208:211], v[46:49]
	v_mfma_f32_16x16x32_bf16 v[46:49], v[176:179], v[212:215], v[46:49]
	v_mfma_f32_16x16x32_bf16 v[30:33], v[172:175], v[216:219], v[30:33]
	v_mfma_f32_16x16x32_bf16 v[30:33], v[176:179], v[220:223], v[30:33]
	v_mfma_f32_16x16x32_bf16 v[14:17], v[172:175], v[224:227], v[14:17]
	v_mfma_f32_16x16x32_bf16 v[14:17], v[176:179], v[228:231], v[14:17]
	v_mfma_f32_16x16x32_bf16 v[50:53], v[184:187], v[200:203], v[50:53]
	v_mfma_f32_16x16x32_bf16 v[50:53], v[188:191], v[204:207], v[50:53]
	v_mfma_f32_16x16x32_bf16 v[34:37], v[184:187], v[208:211], v[34:37]
	v_mfma_f32_16x16x32_bf16 v[34:37], v[188:191], v[212:215], v[34:37]
	v_mfma_f32_16x16x32_bf16 v[18:21], v[184:187], v[216:219], v[18:21]
	v_mfma_f32_16x16x32_bf16 v[18:21], v[188:191], v[220:223], v[18:21]
	v_mfma_f32_16x16x32_bf16 v[6:9], v[184:187], v[224:227], v[6:9]
	v_mfma_f32_16x16x32_bf16 v[6:9], v[188:191], v[228:231], v[6:9]
	v_mfma_f32_16x16x32_bf16 v[42:45], v[192:195], v[200:203], v[42:45]
	v_mfma_f32_16x16x32_bf16 v[42:45], v[196:199], v[204:207], v[42:45]
	v_mfma_f32_16x16x32_bf16 v[26:29], v[192:195], v[208:211], v[26:29]
	v_mfma_f32_16x16x32_bf16 v[26:29], v[196:199], v[212:215], v[26:29]
	v_mfma_f32_16x16x32_bf16 v[10:13], v[192:195], v[216:219], v[10:13]
	v_mfma_f32_16x16x32_bf16 v[10:13], v[196:199], v[220:223], v[10:13]
	v_mfma_f32_16x16x32_bf16 v[2:5], v[192:195], v[224:227], v[2:5]
	v_mfma_f32_16x16x32_bf16 v[2:5], v[196:199], v[228:231], v[2:5]
	s_barrier
	s_add_i32 s83, s83, 2
	s_add_u32 s28, s28, 0x100
	s_addc_u32 s29, s29, 0
	s_add_u32 s81, s81, 0x100
	s_addc_u32 s82, s82, 0
	s_cmp_gt_u32 s83, 61
	s_cbranch_scc0 .LBB0_217
	s_and_b64 vcc, exec, s[16:17]
	s_cbranch_vccz .LBB0_220
	s_barrier

.LBB0_237:
	ds_read_b128 v[148:151], v164
	ds_read_b128 v[168:171], v164 offset:1024
	ds_read_b128 v[172:175], v164 offset:2048
	ds_read_b128 v[176:179], v164 offset:3072
	ds_read_b128 v[184:187], v165
	ds_read_b128 v[188:191], v165 offset:1024
	ds_read_b128 v[192:195], v165 offset:2048
	ds_read_b128 v[196:199], v165 offset:3072
	s_add_u32 s28, s26, 0xfff00080
	s_addc_u32 s29, s27, -1
	s_cmp_eq_u32 s63, 60
	s_cselect_b32 s31, s19, s29
	s_cselect_b32 s30, s53, s28
	s_cselect_b32 s29, s17, s62
	s_cselect_b32 s28, s58, s59
	v_lshl_add_u64 v[152:153], s[26:27], 0, v[140:141]
	s_add_i32 m0, s25, 0xc000
	ds_read_b128 v[200:203], v166
	ds_read_b128 v[204:207], v166 offset:1024
	ds_read_b128 v[208:211], v166 offset:2048
	ds_read_b128 v[212:215], v166 offset:3072
	ds_read_b128 v[216:219], v166 offset:4096
	ds_read_b128 v[220:223], v166 offset:5120
	ds_read_b128 v[224:227], v166 offset:6144
	ds_read_b128 v[228:231], v166 offset:7168
	global_load_lds_dwordx4 v[152:153], off
	v_lshl_add_u64 v[152:153], s[26:27], 0, v[142:143]
	s_add_i32 m0, s25, 0xe000
	s_nop 0
	global_load_lds_dwordx4 v[152:153], off
	s_waitcnt vmcnt(8)
	s_waitcnt lgkmcnt(0)
	s_barrier
	s_waitcnt lgkmcnt(0)
	v_mfma_f32_16x16x32_bf16 v[126:129], v[148:151], v[200:203], v[126:129]
	v_mfma_f32_16x16x32_bf16 v[126:129], v[168:171], v[204:207], v[126:129]
	v_mfma_f32_16x16x32_bf16 v[110:113], v[148:151], v[208:211], v[110:113]
	v_mfma_f32_16x16x32_bf16 v[110:113], v[168:171], v[212:215], v[110:113]
	v_mfma_f32_16x16x32_bf16 v[94:97], v[148:151], v[216:219], v[94:97]
	v_mfma_f32_16x16x32_bf16 v[94:97], v[168:171], v[220:223], v[94:97]
	v_mfma_f32_16x16x32_bf16 v[78:81], v[148:151], v[224:227], v[78:81]
	v_mfma_f32_16x16x32_bf16 v[78:81], v[168:171], v[228:231], v[78:81]
	v_mfma_f32_16x16x32_bf16 v[122:125], v[172:175], v[200:203], v[122:125]
	v_mfma_f32_16x16x32_bf16 v[122:125], v[176:179], v[204:207], v[122:125]
	v_mfma_f32_16x16x32_bf16 v[106:109], v[172:175], v[208:211], v[106:109]
	v_mfma_f32_16x16x32_bf16 v[106:109], v[176:179], v[212:215], v[106:109]
	v_mfma_f32_16x16x32_bf16 v[90:93], v[172:175], v[216:219], v[90:93]
	v_mfma_f32_16x16x32_bf16 v[90:93], v[176:179], v[220:223], v[90:93]
	v_mfma_f32_16x16x32_bf16 v[74:77], v[172:175], v[224:227], v[74:77]
	v_mfma_f32_16x16x32_bf16 v[74:77], v[176:179], v[228:231], v[74:77]
	v_mfma_f32_16x16x32_bf16 v[118:121], v[184:187], v[200:203], v[118:121]
	v_mfma_f32_16x16x32_bf16 v[118:121], v[188:191], v[204:207], v[118:121]
	v_mfma_f32_16x16x32_bf16 v[102:105], v[184:187], v[208:211], v[102:105]
	v_mfma_f32_16x16x32_bf16 v[102:105], v[188:191], v[212:215], v[102:105]
	v_mfma_f32_16x16x32_bf16 v[86:89], v[184:187], v[216:219], v[86:89]
	v_mfma_f32_16x16x32_bf16 v[86:89], v[188:191], v[220:223], v[86:89]
	v_mfma_f32_16x16x32_bf16 v[70:73], v[184:187], v[224:227], v[70:73]
	v_mfma_f32_16x16x32_bf16 v[70:73], v[188:191], v[228:231], v[70:73]
	v_mfma_f32_16x16x32_bf16 v[114:117], v[192:195], v[200:203], v[114:117]
	v_mfma_f32_16x16x32_bf16 v[114:117], v[196:199], v[204:207], v[114:117]
	v_mfma_f32_16x16x32_bf16 v[98:101], v[192:195], v[208:211], v[98:101]
	v_mfma_f32_16x16x32_bf16 v[98:101], v[196:199], v[212:215], v[98:101]
	v_mfma_f32_16x16x32_bf16 v[82:85], v[192:195], v[216:219], v[82:85]
	v_mfma_f32_16x16x32_bf16 v[82:85], v[196:199], v[220:223], v[82:85]
	v_mfma_f32_16x16x32_bf16 v[66:69], v[192:195], v[224:227], v[66:69]
	v_mfma_f32_16x16x32_bf16 v[66:69], v[196:199], v[228:231], v[66:69]
	s_barrier
	s_add_i32 s80, s50, s34
	v_lshl_add_u64 v[152:153], s[28:29], 0, v[132:133]
	s_mov_b32 m0, s80
	ds_read_b128 v[200:203], v166 offset:16384
	ds_read_b128 v[204:207], v166 offset:17408
	ds_read_b128 v[208:211], v166 offset:18432
	ds_read_b128 v[212:215], v166 offset:19456
	ds_read_b128 v[216:219], v166 offset:20480
	ds_read_b128 v[220:223], v166 offset:21504
	ds_read_b128 v[224:227], v166 offset:22528
	ds_read_b128 v[228:231], v166 offset:23552
	global_load_lds_dwordx4 v[152:153], off
	s_add_i32 m0, s80, 0x2000
	s_add_u32 s80, s28, 0x100000
	v_lshl_add_u64 v[180:181], s[28:29], 0, v[136:137]
	s_addc_u32 s81, s29, 0
	s_add_i32 s82, s51, s34
	global_load_lds_dwordx4 v[180:181], off
	v_lshl_add_u64 v[232:233], s[80:81], 0, v[132:133]
	s_mov_b32 m0, s82
	v_lshl_add_u64 v[234:235], s[30:31], 0, v[134:135]
	global_load_lds_dwordx4 v[232:233], off
	v_lshl_add_u64 v[232:233], s[80:81], 0, v[136:137]
	s_add_i32 m0, s82, 0x2000
	s_nop 0
	global_load_lds_dwordx4 v[232:233], off
	v_lshl_add_u64 v[232:233], s[30:31], 0, v[130:131]
	s_mov_b32 m0, s25
	s_nop 0
	global_load_lds_dwordx4 v[232:233], off
	s_mov_b32 m0, s41
	s_nop 0
	global_load_lds_dwordx4 v[234:235], off
	s_waitcnt vmcnt(8)
	s_waitcnt lgkmcnt(0)
	s_barrier
	s_waitcnt lgkmcnt(0)
	v_mfma_f32_16x16x32_bf16 v[62:65], v[148:151], v[200:203], v[62:65]
	v_mfma_f32_16x16x32_bf16 v[62:65], v[168:171], v[204:207], v[62:65]
	v_mfma_f32_16x16x32_bf16 v[46:49], v[148:151], v[208:211], v[46:49]
	v_mfma_f32_16x16x32_bf16 v[46:49], v[168:171], v[212:215], v[46:49]
	v_mfma_f32_16x16x32_bf16 v[30:33], v[148:151], v[216:219], v[30:33]
	v_mfma_f32_16x16x32_bf16 v[30:33], v[168:171], v[220:223], v[30:33]
	v_mfma_f32_16x16x32_bf16 v[14:17], v[148:151], v[224:227], v[14:17]
	v_mfma_f32_16x16x32_bf16 v[14:17], v[168:171], v[228:231], v[14:17]
	v_mfma_f32_16x16x32_bf16 v[58:61], v[172:175], v[200:203], v[58:61]
	v_mfma_f32_16x16x32_bf16 v[58:61], v[176:179], v[204:207], v[58:61]
	v_mfma_f32_16x16x32_bf16 v[42:45], v[172:175], v[208:211], v[42:45]
	v_mfma_f32_16x16x32_bf16 v[42:45], v[176:179], v[212:215], v[42:45]
	v_mfma_f32_16x16x32_bf16 v[26:29], v[172:175], v[216:219], v[26:29]
	v_mfma_f32_16x16x32_bf16 v[26:29], v[176:179], v[220:223], v[26:29]
	v_mfma_f32_16x16x32_bf16 v[10:13], v[172:175], v[224:227], v[10:13]
	v_mfma_f32_16x16x32_bf16 v[10:13], v[176:179], v[228:231], v[10:13]
	v_mfma_f32_16x16x32_bf16 v[54:57], v[184:187], v[200:203], v[54:57]
	v_mfma_f32_16x16x32_bf16 v[54:57], v[188:191], v[204:207], v[54:57]
	v_mfma_f32_16x16x32_bf16 v[38:41], v[184:187], v[208:211], v[38:41]
	v_mfma_f32_16x16x32_bf16 v[38:41], v[188:191], v[212:215], v[38:41]
	v_mfma_f32_16x16x32_bf16 v[22:25], v[184:187], v[216:219], v[22:25]
	v_mfma_f32_16x16x32_bf16 v[22:25], v[188:191], v[220:223], v[22:25]
	v_mfma_f32_16x16x32_bf16 v[6:9], v[184:187], v[224:227], v[6:9]
	v_mfma_f32_16x16x32_bf16 v[6:9], v[188:191], v[228:231], v[6:9]
	v_mfma_f32_16x16x32_bf16 v[50:53], v[192:195], v[200:203], v[50:53]
	v_mfma_f32_16x16x32_bf16 v[50:53], v[196:199], v[204:207], v[50:53]
	v_mfma_f32_16x16x32_bf16 v[34:37], v[192:195], v[208:211], v[34:37]
	v_mfma_f32_16x16x32_bf16 v[34:37], v[196:199], v[212:215], v[34:37]
	v_mfma_f32_16x16x32_bf16 v[18:21], v[192:195], v[216:219], v[18:21]
	v_mfma_f32_16x16x32_bf16 v[18:21], v[196:199], v[220:223], v[18:21]
	v_mfma_f32_16x16x32_bf16 v[2:5], v[192:195], v[224:227], v[2:5]
	v_mfma_f32_16x16x32_bf16 v[2:5], v[196:199], v[228:231], v[2:5]
	s_barrier
	s_add_i32 s80, 0, 0x18000
	v_add_u32_e32 v167, s80, v161
	s_add_i32 s81, 0, 0x1c000
	ds_read_b128 v[148:151], v167
	ds_read_b128 v[168:171], v167 offset:1024
	ds_read_b128 v[172:175], v167 offset:2048
	ds_read_b128 v[176:179], v167 offset:3072
	v_add_u32_e32 v167, s81, v161
	ds_read_b128 v[184:187], v167
	ds_read_b128 v[188:191], v167 offset:1024
	ds_read_b128 v[192:195], v167 offset:2048
	ds_read_b128 v[196:199], v167 offset:3072
	s_add_u32 s30, s30, 0x100000
	s_addc_u32 s31, s31, 0
	s_mov_b32 m0, s42
	v_lshl_add_u64 v[236:237], s[30:31], 0, v[130:131]
	ds_read_b128 v[200:203], v166 offset:32768
	ds_read_b128 v[204:207], v166 offset:33792
	ds_read_b128 v[208:211], v166 offset:34816
	ds_read_b128 v[212:215], v166 offset:35840
	ds_read_b128 v[216:219], v166 offset:36864
	ds_read_b128 v[220:223], v166 offset:37888
	ds_read_b128 v[224:227], v166 offset:38912
	ds_read_b128 v[228:231], v166 offset:39936
	global_load_lds_dwordx4 v[236:237], off
	v_lshl_add_u64 v[236:237], s[30:31], 0, v[134:135]
	s_mov_b32 m0, s44
	s_nop 0
	global_load_lds_dwordx4 v[236:237], off
	s_waitcnt vmcnt(8)
	s_waitcnt lgkmcnt(0)
	s_barrier
	s_waitcnt lgkmcnt(0)
	v_mfma_f32_16x16x32_bf16 v[126:129], v[148:151], v[200:203], v[126:129]
	v_mfma_f32_16x16x32_bf16 v[126:129], v[168:171], v[204:207], v[126:129]
	v_mfma_f32_16x16x32_bf16 v[110:113], v[148:151], v[208:211], v[110:113]
	v_mfma_f32_16x16x32_bf16 v[110:113], v[168:171], v[212:215], v[110:113]
	v_mfma_f32_16x16x32_bf16 v[94:97], v[148:151], v[216:219], v[94:97]
	v_mfma_f32_16x16x32_bf16 v[94:97], v[168:171], v[220:223], v[94:97]
	v_mfma_f32_16x16x32_bf16 v[78:81], v[148:151], v[224:227], v[78:81]
	v_mfma_f32_16x16x32_bf16 v[78:81], v[168:171], v[228:231], v[78:81]
	v_mfma_f32_16x16x32_bf16 v[122:125], v[172:175], v[200:203], v[122:125]
	v_mfma_f32_16x16x32_bf16 v[122:125], v[176:179], v[204:207], v[122:125]
	v_mfma_f32_16x16x32_bf16 v[106:109], v[172:175], v[208:211], v[106:109]
	v_mfma_f32_16x16x32_bf16 v[106:109], v[176:179], v[212:215], v[106:109]
	v_mfma_f32_16x16x32_bf16 v[90:93], v[172:175], v[216:219], v[90:93]
	v_mfma_f32_16x16x32_bf16 v[90:93], v[176:179], v[220:223], v[90:93]
	v_mfma_f32_16x16x32_bf16 v[74:77], v[172:175], v[224:227], v[74:77]
	v_mfma_f32_16x16x32_bf16 v[74:77], v[176:179], v[228:231], v[74:77]
	v_mfma_f32_16x16x32_bf16 v[118:121], v[184:187], v[200:203], v[118:121]
	v_mfma_f32_16x16x32_bf16 v[118:121], v[188:191], v[204:207], v[118:121]
	v_mfma_f32_16x16x32_bf16 v[102:105], v[184:187], v[208:211], v[102:105]
	v_mfma_f32_16x16x32_bf16 v[102:105], v[188:191], v[212:215], v[102:105]
	v_mfma_f32_16x16x32_bf16 v[86:89], v[184:187], v[216:219], v[86:89]
	v_mfma_f32_16x16x32_bf16 v[86:89], v[188:191], v[220:223], v[86:89]
	v_mfma_f32_16x16x32_bf16 v[70:73], v[184:187], v[224:227], v[70:73]
	v_mfma_f32_16x16x32_bf16 v[70:73], v[188:191], v[228:231], v[70:73]
	v_mfma_f32_16x16x32_bf16 v[114:117], v[192:195], v[200:203], v[114:117]
	v_mfma_f32_16x16x32_bf16 v[114:117], v[196:199], v[204:207], v[114:117]
	v_mfma_f32_16x16x32_bf16 v[98:101], v[192:195], v[208:211], v[98:101]
	v_mfma_f32_16x16x32_bf16 v[98:101], v[196:199], v[212:215], v[98:101]
	v_mfma_f32_16x16x32_bf16 v[82:85], v[192:195], v[216:219], v[82:85]
	v_mfma_f32_16x16x32_bf16 v[82:85], v[196:199], v[220:223], v[82:85]
	v_mfma_f32_16x16x32_bf16 v[66:69], v[192:195], v[224:227], v[66:69]
	v_mfma_f32_16x16x32_bf16 v[66:69], v[196:199], v[228:231], v[66:69]
	s_barrier
	s_add_i32 s30, s80, s34
	v_lshl_add_u64 v[152:153], v[152:153], 0, s[12:13]
	s_mov_b32 m0, s30
	ds_read_b128 v[200:203], v166 offset:49152
	ds_read_b128 v[204:207], v166 offset:50176
	ds_read_b128 v[208:211], v166 offset:51200
	ds_read_b128 v[212:215], v166 offset:52224
	ds_read_b128 v[216:219], v166 offset:53248
	ds_read_b128 v[220:223], v166 offset:54272
	ds_read_b128 v[224:227], v166 offset:55296
	ds_read_b128 v[228:231], v166 offset:56320
	global_load_lds_dwordx4 v[152:153], off
	s_add_i32 m0, s30, 0x2000
	s_add_u32 s28, s28, 0x100080
	v_lshl_add_u64 v[152:153], v[180:181], 0, s[12:13]
	s_addc_u32 s29, s29, 0
	s_add_i32 s30, s81, s34
	global_load_lds_dwordx4 v[152:153], off
	v_lshl_add_u64 v[152:153], s[28:29], 0, v[132:133]
	s_mov_b32 m0, s30
	s_nop 0
	global_load_lds_dwordx4 v[152:153], off
	v_lshl_add_u64 v[152:153], s[28:29], 0, v[136:137]
	s_add_i32 m0, s30, 0x2000
	s_nop 0
	global_load_lds_dwordx4 v[152:153], off
	v_lshl_add_u64 v[152:153], v[232:233], 0, s[12:13]
	s_mov_b32 m0, s46
	s_nop 0
	global_load_lds_dwordx4 v[152:153], off
	v_lshl_add_u64 v[152:153], v[234:235], 0, s[12:13]
	s_mov_b32 m0, s47
	s_nop 0
	global_load_lds_dwordx4 v[152:153], off
	s_waitcnt vmcnt(8)
	s_waitcnt lgkmcnt(0)
	s_barrier
	s_waitcnt lgkmcnt(0)
	v_mfma_f32_16x16x32_bf16 v[62:65], v[148:151], v[200:203], v[62:65]
	v_mfma_f32_16x16x32_bf16 v[62:65], v[168:171], v[204:207], v[62:65]
	v_mfma_f32_16x16x32_bf16 v[46:49], v[148:151], v[208:211], v[46:49]
	v_mfma_f32_16x16x32_bf16 v[46:49], v[168:171], v[212:215], v[46:49]
	v_mfma_f32_16x16x32_bf16 v[30:33], v[148:151], v[216:219], v[30:33]
	v_mfma_f32_16x16x32_bf16 v[30:33], v[168:171], v[220:223], v[30:33]
	v_mfma_f32_16x16x32_bf16 v[14:17], v[148:151], v[224:227], v[14:17]
	v_mfma_f32_16x16x32_bf16 v[14:17], v[168:171], v[228:231], v[14:17]
	v_mfma_f32_16x16x32_bf16 v[58:61], v[172:175], v[200:203], v[58:61]
	v_mfma_f32_16x16x32_bf16 v[58:61], v[176:179], v[204:207], v[58:61]
	v_mfma_f32_16x16x32_bf16 v[42:45], v[172:175], v[208:211], v[42:45]
	v_mfma_f32_16x16x32_bf16 v[42:45], v[176:179], v[212:215], v[42:45]
	v_mfma_f32_16x16x32_bf16 v[26:29], v[172:175], v[216:219], v[26:29]
	v_mfma_f32_16x16x32_bf16 v[26:29], v[176:179], v[220:223], v[26:29]
	v_mfma_f32_16x16x32_bf16 v[10:13], v[172:175], v[224:227], v[10:13]
	v_mfma_f32_16x16x32_bf16 v[10:13], v[176:179], v[228:231], v[10:13]
	v_mfma_f32_16x16x32_bf16 v[54:57], v[184:187], v[200:203], v[54:57]
	v_mfma_f32_16x16x32_bf16 v[54:57], v[188:191], v[204:207], v[54:57]
	v_mfma_f32_16x16x32_bf16 v[38:41], v[184:187], v[208:211], v[38:41]
	v_mfma_f32_16x16x32_bf16 v[38:41], v[188:191], v[212:215], v[38:41]
	v_mfma_f32_16x16x32_bf16 v[22:25], v[184:187], v[216:219], v[22:25]
	v_mfma_f32_16x16x32_bf16 v[22:25], v[188:191], v[220:223], v[22:25]
	v_mfma_f32_16x16x32_bf16 v[6:9], v[184:187], v[224:227], v[6:9]
	v_mfma_f32_16x16x32_bf16 v[6:9], v[188:191], v[228:231], v[6:9]
	v_mfma_f32_16x16x32_bf16 v[50:53], v[192:195], v[200:203], v[50:53]
	v_mfma_f32_16x16x32_bf16 v[50:53], v[196:199], v[204:207], v[50:53]
	v_mfma_f32_16x16x32_bf16 v[34:37], v[192:195], v[208:211], v[34:37]
	v_mfma_f32_16x16x32_bf16 v[34:37], v[196:199], v[212:215], v[34:37]
	v_mfma_f32_16x16x32_bf16 v[18:21], v[192:195], v[216:219], v[18:21]
	v_mfma_f32_16x16x32_bf16 v[18:21], v[196:199], v[220:223], v[18:21]
	v_mfma_f32_16x16x32_bf16 v[2:5], v[192:195], v[224:227], v[2:5]
	v_mfma_f32_16x16x32_bf16 v[2:5], v[196:199], v[228:231], v[2:5]
	s_barrier
	s_add_i32 s63, s63, 2
	s_add_u32 s26, s26, 0x100
	s_addc_u32 s27, s27, 0
	s_add_u32 s59, s59, 0x100
	s_addc_u32 s62, s62, 0
	s_cmp_gt_u32 s63, 61
	s_cbranch_scc0 .LBB0_237
	s_and_b64 vcc, exec, s[14:15]
	s_cbranch_vccz .LBB0_240
	s_barrier

.LBB0_269:
	v_add_u32_e32 v147, s46, v161
	ds_read_b128 v[166:169], v147
	ds_read_b128 v[170:173], v147 offset:1024
	ds_read_b128 v[174:177], v147 offset:2048
	ds_read_b128 v[178:181], v147 offset:3072
	v_add_u32_e32 v147, s47, v161
	ds_read_b128 v[184:187], v147
	ds_read_b128 v[188:191], v147 offset:1024
	ds_read_b128 v[192:195], v147 offset:2048
	ds_read_b128 v[196:199], v147 offset:3072
	s_mov_b32 s34, 0xfff00080
	s_cmp_eq_u32 s30, 60
	s_mov_b32 s35, -1
	v_lshl_add_u64 v[200:201], v[156:157], 0, s[34:35]
	s_cselect_b64 vcc, -1, 0
	v_cndmask_b32_e32 v233, v201, v1, vcc
	v_cndmask_b32_e32 v232, v200, v152, vcc
	v_cndmask_b32_e32 v235, v159, v145, vcc
	v_cndmask_b32_e32 v234, v158, v154, vcc
	v_lshl_add_u64 v[236:237], v[156:157], 0, v[138:139]
	s_add_i32 m0, s39, 0xc000
	ds_read_b128 v[200:203], v155
	ds_read_b128 v[204:207], v155 offset:1024
	ds_read_b128 v[208:211], v155 offset:2048
	ds_read_b128 v[212:215], v155 offset:3072
	ds_read_b128 v[216:219], v155 offset:4096
	ds_read_b128 v[220:223], v155 offset:5120
	ds_read_b128 v[224:227], v155 offset:6144
	ds_read_b128 v[228:231], v155 offset:7168
	global_load_lds_dwordx4 v[236:237], off
	v_lshl_add_u64 v[236:237], v[156:157], 0, v[140:141]
	s_add_i32 m0, s39, 0xe000
	s_nop 0
	global_load_lds_dwordx4 v[236:237], off
	s_waitcnt vmcnt(8)
	s_waitcnt lgkmcnt(0)
	s_barrier
	s_waitcnt lgkmcnt(0)
	v_mfma_f32_16x16x32_bf16 v[126:129], v[166:169], v[200:203], v[126:129]
	v_mfma_f32_16x16x32_bf16 v[126:129], v[170:173], v[204:207], v[126:129]
	v_mfma_f32_16x16x32_bf16 v[118:121], v[166:169], v[208:211], v[118:121]
	v_mfma_f32_16x16x32_bf16 v[118:121], v[170:173], v[212:215], v[118:121]
	v_mfma_f32_16x16x32_bf16 v[102:105], v[166:169], v[216:219], v[102:105]
	v_mfma_f32_16x16x32_bf16 v[102:105], v[170:173], v[220:223], v[102:105]
	v_mfma_f32_16x16x32_bf16 v[86:89], v[166:169], v[224:227], v[86:89]
	v_mfma_f32_16x16x32_bf16 v[86:89], v[170:173], v[228:231], v[86:89]
	v_mfma_f32_16x16x32_bf16 v[122:125], v[174:177], v[200:203], v[122:125]
	v_mfma_f32_16x16x32_bf16 v[122:125], v[178:181], v[204:207], v[122:125]
	v_mfma_f32_16x16x32_bf16 v[110:113], v[174:177], v[208:211], v[110:113]
	v_mfma_f32_16x16x32_bf16 v[110:113], v[178:181], v[212:215], v[110:113]
	v_mfma_f32_16x16x32_bf16 v[94:97], v[174:177], v[216:219], v[94:97]
	v_mfma_f32_16x16x32_bf16 v[94:97], v[178:181], v[220:223], v[94:97]
	v_mfma_f32_16x16x32_bf16 v[78:81], v[174:177], v[224:227], v[78:81]
	v_mfma_f32_16x16x32_bf16 v[78:81], v[178:181], v[228:231], v[78:81]
	v_mfma_f32_16x16x32_bf16 v[114:117], v[184:187], v[200:203], v[114:117]
	v_mfma_f32_16x16x32_bf16 v[114:117], v[188:191], v[204:207], v[114:117]
	v_mfma_f32_16x16x32_bf16 v[98:101], v[184:187], v[208:211], v[98:101]
	v_mfma_f32_16x16x32_bf16 v[98:101], v[188:191], v[212:215], v[98:101]
	v_mfma_f32_16x16x32_bf16 v[82:85], v[184:187], v[216:219], v[82:85]
	v_mfma_f32_16x16x32_bf16 v[82:85], v[188:191], v[220:223], v[82:85]
	v_mfma_f32_16x16x32_bf16 v[70:73], v[184:187], v[224:227], v[70:73]
	v_mfma_f32_16x16x32_bf16 v[70:73], v[188:191], v[228:231], v[70:73]
	v_mfma_f32_16x16x32_bf16 v[106:109], v[192:195], v[200:203], v[106:109]
	v_mfma_f32_16x16x32_bf16 v[106:109], v[196:199], v[204:207], v[106:109]
	v_mfma_f32_16x16x32_bf16 v[90:93], v[192:195], v[208:211], v[90:93]
	v_mfma_f32_16x16x32_bf16 v[90:93], v[196:199], v[212:215], v[90:93]
	v_mfma_f32_16x16x32_bf16 v[74:77], v[192:195], v[216:219], v[74:77]
	v_mfma_f32_16x16x32_bf16 v[74:77], v[196:199], v[220:223], v[74:77]
	v_mfma_f32_16x16x32_bf16 v[66:69], v[192:195], v[224:227], v[66:69]
	v_mfma_f32_16x16x32_bf16 v[66:69], v[196:199], v[228:231], v[66:69]
	s_barrier
	s_add_i32 s31, s46, s38
	v_lshl_add_u64 v[236:237], v[234:235], 0, v[132:133]
	s_mov_b32 m0, s31
	ds_read_b128 v[200:203], v155 offset:16384
	ds_read_b128 v[204:207], v155 offset:17408
	ds_read_b128 v[208:211], v155 offset:18432
	ds_read_b128 v[212:215], v155 offset:19456
	ds_read_b128 v[216:219], v155 offset:20480
	ds_read_b128 v[220:223], v155 offset:21504
	ds_read_b128 v[224:227], v155 offset:22528
	ds_read_b128 v[228:231], v155 offset:23552
	global_load_lds_dwordx4 v[236:237], off
	v_lshl_add_u64 v[238:239], v[234:235], 0, v[136:137]
	s_add_i32 m0, s31, 0x2000
	v_lshl_add_u64 v[240:241], v[234:235], 0, s[6:7]
	s_add_i32 s31, s47, s38
	global_load_lds_dwordx4 v[238:239], off
	v_lshl_add_u64 v[242:243], v[240:241], 0, v[132:133]
	s_mov_b32 m0, s31
	v_lshl_add_u64 v[240:241], v[240:241], 0, v[136:137]
	global_load_lds_dwordx4 v[242:243], off
	s_add_i32 m0, s31, 0x2000
	v_lshl_add_u64 v[242:243], v[232:233], 0, v[134:135]
	global_load_lds_dwordx4 v[240:241], off
	v_lshl_add_u64 v[240:241], v[232:233], 0, v[130:131]
	s_mov_b32 m0, s39
	s_nop 0
	global_load_lds_dwordx4 v[240:241], off
	s_mov_b32 m0, s40
	s_nop 0
	global_load_lds_dwordx4 v[242:243], off
	s_waitcnt vmcnt(8)
	s_waitcnt lgkmcnt(0)
	s_barrier
	s_waitcnt lgkmcnt(0)
	v_mfma_f32_16x16x32_bf16 v[62:65], v[166:169], v[200:203], v[62:65]
	v_mfma_f32_16x16x32_bf16 v[62:65], v[170:173], v[204:207], v[62:65]
	v_mfma_f32_16x16x32_bf16 v[54:57], v[166:169], v[208:211], v[54:57]
	v_mfma_f32_16x16x32_bf16 v[54:57], v[170:173], v[212:215], v[54:57]
	v_mfma_f32_16x16x32_bf16 v[38:41], v[166:169], v[216:219], v[38:41]
	v_mfma_f32_16x16x32_bf16 v[38:41], v[170:173], v[220:223], v[38:41]
	v_mfma_f32_16x16x32_bf16 v[22:25], v[166:169], v[224:227], v[22:25]
	v_mfma_f32_16x16x32_bf16 v[22:25], v[170:173], v[228:231], v[22:25]
	v_mfma_f32_16x16x32_bf16 v[58:61], v[174:177], v[200:203], v[58:61]
	v_mfma_f32_16x16x32_bf16 v[58:61], v[178:181], v[204:207], v[58:61]
	v_mfma_f32_16x16x32_bf16 v[46:49], v[174:177], v[208:211], v[46:49]
	v_mfma_f32_16x16x32_bf16 v[46:49], v[178:181], v[212:215], v[46:49]
	v_mfma_f32_16x16x32_bf16 v[30:33], v[174:177], v[216:219], v[30:33]
	v_mfma_f32_16x16x32_bf16 v[30:33], v[178:181], v[220:223], v[30:33]
	v_mfma_f32_16x16x32_bf16 v[14:17], v[174:177], v[224:227], v[14:17]
	v_mfma_f32_16x16x32_bf16 v[14:17], v[178:181], v[228:231], v[14:17]
	v_mfma_f32_16x16x32_bf16 v[50:53], v[184:187], v[200:203], v[50:53]
	v_mfma_f32_16x16x32_bf16 v[50:53], v[188:191], v[204:207], v[50:53]
	v_mfma_f32_16x16x32_bf16 v[34:37], v[184:187], v[208:211], v[34:37]
	v_mfma_f32_16x16x32_bf16 v[34:37], v[188:191], v[212:215], v[34:37]
	v_mfma_f32_16x16x32_bf16 v[18:21], v[184:187], v[216:219], v[18:21]
	v_mfma_f32_16x16x32_bf16 v[18:21], v[188:191], v[220:223], v[18:21]
	v_mfma_f32_16x16x32_bf16 v[6:9], v[184:187], v[224:227], v[6:9]
	v_mfma_f32_16x16x32_bf16 v[6:9], v[188:191], v[228:231], v[6:9]
	v_mfma_f32_16x16x32_bf16 v[42:45], v[192:195], v[200:203], v[42:45]
	v_mfma_f32_16x16x32_bf16 v[42:45], v[196:199], v[204:207], v[42:45]
	v_mfma_f32_16x16x32_bf16 v[26:29], v[192:195], v[208:211], v[26:29]
	v_mfma_f32_16x16x32_bf16 v[26:29], v[196:199], v[212:215], v[26:29]
	v_mfma_f32_16x16x32_bf16 v[10:13], v[192:195], v[216:219], v[10:13]
	v_mfma_f32_16x16x32_bf16 v[10:13], v[196:199], v[220:223], v[10:13]
	v_mfma_f32_16x16x32_bf16 v[2:5], v[192:195], v[224:227], v[2:5]
	v_mfma_f32_16x16x32_bf16 v[2:5], v[196:199], v[228:231], v[2:5]
	s_barrier
	s_add_i32 s31, 0, 0x18000
	v_add_u32_e32 v147, s31, v161
	s_add_i32 s34, 0, 0x1c000
	ds_read_b128 v[166:169], v147
	ds_read_b128 v[170:173], v147 offset:1024
	ds_read_b128 v[174:177], v147 offset:2048
	ds_read_b128 v[178:181], v147 offset:3072
	v_add_u32_e32 v147, s34, v161
	ds_read_b128 v[184:187], v147
	ds_read_b128 v[188:191], v147 offset:1024
	ds_read_b128 v[192:195], v147 offset:2048
	ds_read_b128 v[196:199], v147 offset:3072
	v_lshl_add_u64 v[232:233], v[232:233], 0, s[6:7]
	s_mov_b32 m0, s41
	v_lshl_add_u64 v[244:245], v[232:233], 0, v[130:131]
	ds_read_b128 v[200:203], v155 offset:32768
	ds_read_b128 v[204:207], v155 offset:33792
	ds_read_b128 v[208:211], v155 offset:34816
	ds_read_b128 v[212:215], v155 offset:35840
	ds_read_b128 v[216:219], v155 offset:36864
	ds_read_b128 v[220:223], v155 offset:37888
	ds_read_b128 v[224:227], v155 offset:38912
	ds_read_b128 v[228:231], v155 offset:39936
	global_load_lds_dwordx4 v[244:245], off
	v_lshl_add_u64 v[232:233], v[232:233], 0, v[134:135]
	s_mov_b32 m0, s42
	s_nop 0
	global_load_lds_dwordx4 v[232:233], off
	s_waitcnt vmcnt(8)
	s_waitcnt lgkmcnt(0)
	s_barrier
	s_waitcnt lgkmcnt(0)
	v_mfma_f32_16x16x32_bf16 v[126:129], v[166:169], v[200:203], v[126:129]
	v_mfma_f32_16x16x32_bf16 v[126:129], v[170:173], v[204:207], v[126:129]
	v_mfma_f32_16x16x32_bf16 v[118:121], v[166:169], v[208:211], v[118:121]
	v_mfma_f32_16x16x32_bf16 v[118:121], v[170:173], v[212:215], v[118:121]
	v_mfma_f32_16x16x32_bf16 v[102:105], v[166:169], v[216:219], v[102:105]
	v_mfma_f32_16x16x32_bf16 v[102:105], v[170:173], v[220:223], v[102:105]
	v_mfma_f32_16x16x32_bf16 v[86:89], v[166:169], v[224:227], v[86:89]
	v_mfma_f32_16x16x32_bf16 v[86:89], v[170:173], v[228:231], v[86:89]
	v_mfma_f32_16x16x32_bf16 v[122:125], v[174:177], v[200:203], v[122:125]
	v_mfma_f32_16x16x32_bf16 v[122:125], v[178:181], v[204:207], v[122:125]
	v_mfma_f32_16x16x32_bf16 v[110:113], v[174:177], v[208:211], v[110:113]
	v_mfma_f32_16x16x32_bf16 v[110:113], v[178:181], v[212:215], v[110:113]
	v_mfma_f32_16x16x32_bf16 v[94:97], v[174:177], v[216:219], v[94:97]
	v_mfma_f32_16x16x32_bf16 v[94:97], v[178:181], v[220:223], v[94:97]
	v_mfma_f32_16x16x32_bf16 v[78:81], v[174:177], v[224:227], v[78:81]
	v_mfma_f32_16x16x32_bf16 v[78:81], v[178:181], v[228:231], v[78:81]
	v_mfma_f32_16x16x32_bf16 v[114:117], v[184:187], v[200:203], v[114:117]
	v_mfma_f32_16x16x32_bf16 v[114:117], v[188:191], v[204:207], v[114:117]
	v_mfma_f32_16x16x32_bf16 v[98:101], v[184:187], v[208:211], v[98:101]
	v_mfma_f32_16x16x32_bf16 v[98:101], v[188:191], v[212:215], v[98:101]
	v_mfma_f32_16x16x32_bf16 v[82:85], v[184:187], v[216:219], v[82:85]
	v_mfma_f32_16x16x32_bf16 v[82:85], v[188:191], v[220:223], v[82:85]
	v_mfma_f32_16x16x32_bf16 v[70:73], v[184:187], v[224:227], v[70:73]
	v_mfma_f32_16x16x32_bf16 v[70:73], v[188:191], v[228:231], v[70:73]
	v_mfma_f32_16x16x32_bf16 v[106:109], v[192:195], v[200:203], v[106:109]
	v_mfma_f32_16x16x32_bf16 v[106:109], v[196:199], v[204:207], v[106:109]
	v_mfma_f32_16x16x32_bf16 v[90:93], v[192:195], v[208:211], v[90:93]
	v_mfma_f32_16x16x32_bf16 v[90:93], v[196:199], v[212:215], v[90:93]
	v_mfma_f32_16x16x32_bf16 v[74:77], v[192:195], v[216:219], v[74:77]
	v_mfma_f32_16x16x32_bf16 v[74:77], v[196:199], v[220:223], v[74:77]
	v_mfma_f32_16x16x32_bf16 v[66:69], v[192:195], v[224:227], v[66:69]
	v_mfma_f32_16x16x32_bf16 v[66:69], v[196:199], v[228:231], v[66:69]
	s_barrier
	s_add_i32 s31, s31, s38
	v_lshl_add_u64 v[232:233], v[236:237], 0, s[12:13]
	s_mov_b32 m0, s31
	ds_read_b128 v[200:203], v155 offset:49152
	ds_read_b128 v[204:207], v155 offset:50176
	ds_read_b128 v[208:211], v155 offset:51200
	ds_read_b128 v[212:215], v155 offset:52224
	ds_read_b128 v[216:219], v155 offset:53248
	ds_read_b128 v[220:223], v155 offset:54272
	ds_read_b128 v[224:227], v155 offset:55296
	ds_read_b128 v[228:231], v155 offset:56320
	global_load_lds_dwordx4 v[232:233], off
	v_lshl_add_u64 v[232:233], v[238:239], 0, s[12:13]
	s_add_i32 m0, s31, 0x2000
	s_add_i32 s31, s34, s38
	global_load_lds_dwordx4 v[232:233], off
	v_lshl_add_u64 v[232:233], v[234:235], 0, s[16:17]
	v_lshl_add_u64 v[234:235], v[232:233], 0, v[132:133]
	s_mov_b32 m0, s31
	v_lshl_add_u64 v[232:233], v[232:233], 0, v[136:137]
	global_load_lds_dwordx4 v[234:235], off
	s_add_i32 m0, s31, 0x2000
	s_nop 0
	global_load_lds_dwordx4 v[232:233], off
	v_lshl_add_u64 v[232:233], v[240:241], 0, s[12:13]
	s_mov_b32 m0, s44
	s_nop 0
	global_load_lds_dwordx4 v[232:233], off
	v_lshl_add_u64 v[232:233], v[242:243], 0, s[12:13]
	s_mov_b32 m0, s45
	s_nop 0
	global_load_lds_dwordx4 v[232:233], off
	s_waitcnt vmcnt(8)
	s_waitcnt lgkmcnt(0)
	s_barrier
	s_waitcnt lgkmcnt(0)
	v_mfma_f32_16x16x32_bf16 v[62:65], v[166:169], v[200:203], v[62:65]
	v_mfma_f32_16x16x32_bf16 v[62:65], v[170:173], v[204:207], v[62:65]
	v_mfma_f32_16x16x32_bf16 v[54:57], v[166:169], v[208:211], v[54:57]
	v_mfma_f32_16x16x32_bf16 v[54:57], v[170:173], v[212:215], v[54:57]
	v_mfma_f32_16x16x32_bf16 v[38:41], v[166:169], v[216:219], v[38:41]
	v_mfma_f32_16x16x32_bf16 v[38:41], v[170:173], v[220:223], v[38:41]
	v_mfma_f32_16x16x32_bf16 v[22:25], v[166:169], v[224:227], v[22:25]
	v_mfma_f32_16x16x32_bf16 v[22:25], v[170:173], v[228:231], v[22:25]
	v_mfma_f32_16x16x32_bf16 v[58:61], v[174:177], v[200:203], v[58:61]
	v_mfma_f32_16x16x32_bf16 v[58:61], v[178:181], v[204:207], v[58:61]
	v_mfma_f32_16x16x32_bf16 v[46:49], v[174:177], v[208:211], v[46:49]
	v_mfma_f32_16x16x32_bf16 v[46:49], v[178:181], v[212:215], v[46:49]
	v_mfma_f32_16x16x32_bf16 v[30:33], v[174:177], v[216:219], v[30:33]
	v_mfma_f32_16x16x32_bf16 v[30:33], v[178:181], v[220:223], v[30:33]
	v_mfma_f32_16x16x32_bf16 v[14:17], v[174:177], v[224:227], v[14:17]
	v_mfma_f32_16x16x32_bf16 v[14:17], v[178:181], v[228:231], v[14:17]
	v_mfma_f32_16x16x32_bf16 v[50:53], v[184:187], v[200:203], v[50:53]
	v_mfma_f32_16x16x32_bf16 v[50:53], v[188:191], v[204:207], v[50:53]
	v_mfma_f32_16x16x32_bf16 v[34:37], v[184:187], v[208:211], v[34:37]
	v_mfma_f32_16x16x32_bf16 v[34:37], v[188:191], v[212:215], v[34:37]
	v_mfma_f32_16x16x32_bf16 v[18:21], v[184:187], v[216:219], v[18:21]
	v_mfma_f32_16x16x32_bf16 v[18:21], v[188:191], v[220:223], v[18:21]
	v_mfma_f32_16x16x32_bf16 v[6:9], v[184:187], v[224:227], v[6:9]
	v_mfma_f32_16x16x32_bf16 v[6:9], v[188:191], v[228:231], v[6:9]
	v_mfma_f32_16x16x32_bf16 v[42:45], v[192:195], v[200:203], v[42:45]
	v_mfma_f32_16x16x32_bf16 v[42:45], v[196:199], v[204:207], v[42:45]
	v_mfma_f32_16x16x32_bf16 v[26:29], v[192:195], v[208:211], v[26:29]
	v_mfma_f32_16x16x32_bf16 v[26:29], v[196:199], v[212:215], v[26:29]
	v_mfma_f32_16x16x32_bf16 v[10:13], v[192:195], v[216:219], v[10:13]
	v_mfma_f32_16x16x32_bf16 v[10:13], v[196:199], v[220:223], v[10:13]
	v_mfma_f32_16x16x32_bf16 v[2:5], v[192:195], v[224:227], v[2:5]
	v_mfma_f32_16x16x32_bf16 v[2:5], v[196:199], v[228:231], v[2:5]
	s_barrier
	s_add_i32 s30, s30, 2
	v_lshl_add_u64 v[156:157], v[156:157], 0, s[22:23]
	s_cmp_gt_u32 s30, 61
	v_lshl_add_u64 v[158:159], v[158:159], 0, s[22:23]
	s_cbranch_scc0 .LBB0_269
	s_and_b64 vcc, exec, s[18:19]
	s_cbranch_vccz .LBB0_272
	s_barrier

.LBB0_763:
	ds_read_b128 v[142:145], v165
	ds_read_b128 v[146:149], v165 offset:1024
	ds_read_b128 v[150:153], v165 offset:2048
	ds_read_b128 v[154:157], v165 offset:3072
	ds_read_b128 v[158:161], v166
	ds_read_b128 v[168:171], v166 offset:1024
	ds_read_b128 v[172:175], v166 offset:2048
	ds_read_b128 v[176:179], v166 offset:3072
	s_add_u32 s28, s26, 0xffe00080
	s_addc_u32 s29, s27, -1
	s_cmpk_eq_i32 s59, 0x7c
	s_cselect_b32 s31, s19, s29
	s_cselect_b32 s30, s53, s28
	s_cselect_b32 s29, s17, s58
	s_cselect_b32 s28, s56, s57
	v_lshl_add_u64 v[180:181], s[26:27], 0, v[134:135]
	s_add_i32 m0, s25, 0xc000
	ds_read_b128 v[184:187], v167
	ds_read_b128 v[188:191], v167 offset:1024
	ds_read_b128 v[192:195], v167 offset:2048
	ds_read_b128 v[196:199], v167 offset:3072
	ds_read_b128 v[200:203], v167 offset:4096
	ds_read_b128 v[204:207], v167 offset:5120
	ds_read_b128 v[208:211], v167 offset:6144
	ds_read_b128 v[212:215], v167 offset:7168
	global_load_lds_dwordx4 v[180:181], off
	v_lshl_add_u64 v[180:181], s[26:27], 0, v[136:137]
	s_add_i32 m0, s25, 0xe000
	s_nop 0
	global_load_lds_dwordx4 v[180:181], off
	s_waitcnt vmcnt(8)
	s_waitcnt lgkmcnt(0)
	s_barrier
	s_waitcnt lgkmcnt(0)
	v_mfma_f32_16x16x32_bf16 v[126:129], v[142:145], v[184:187], v[126:129]
	v_mfma_f32_16x16x32_bf16 v[126:129], v[146:149], v[188:191], v[126:129]
	v_mfma_f32_16x16x32_bf16 v[114:117], v[142:145], v[192:195], v[114:117]
	v_mfma_f32_16x16x32_bf16 v[114:117], v[146:149], v[196:199], v[114:117]
	v_mfma_f32_16x16x32_bf16 v[98:101], v[142:145], v[200:203], v[98:101]
	v_mfma_f32_16x16x32_bf16 v[98:101], v[146:149], v[204:207], v[98:101]
	v_mfma_f32_16x16x32_bf16 v[82:85], v[142:145], v[208:211], v[82:85]
	v_mfma_f32_16x16x32_bf16 v[82:85], v[146:149], v[212:215], v[82:85]
	v_mfma_f32_16x16x32_bf16 v[122:125], v[150:153], v[184:187], v[122:125]
	v_mfma_f32_16x16x32_bf16 v[122:125], v[154:157], v[188:191], v[122:125]
	v_mfma_f32_16x16x32_bf16 v[106:109], v[150:153], v[192:195], v[106:109]
	v_mfma_f32_16x16x32_bf16 v[106:109], v[154:157], v[196:199], v[106:109]
	v_mfma_f32_16x16x32_bf16 v[90:93], v[150:153], v[200:203], v[90:93]
	v_mfma_f32_16x16x32_bf16 v[90:93], v[154:157], v[204:207], v[90:93]
	v_mfma_f32_16x16x32_bf16 v[74:77], v[150:153], v[208:211], v[74:77]
	v_mfma_f32_16x16x32_bf16 v[74:77], v[154:157], v[212:215], v[74:77]
	v_mfma_f32_16x16x32_bf16 v[118:121], v[158:161], v[184:187], v[118:121]
	v_mfma_f32_16x16x32_bf16 v[118:121], v[168:171], v[188:191], v[118:121]
	v_mfma_f32_16x16x32_bf16 v[102:105], v[158:161], v[192:195], v[102:105]
	v_mfma_f32_16x16x32_bf16 v[102:105], v[168:171], v[196:199], v[102:105]
	v_mfma_f32_16x16x32_bf16 v[86:89], v[158:161], v[200:203], v[86:89]
	v_mfma_f32_16x16x32_bf16 v[86:89], v[168:171], v[204:207], v[86:89]
	v_mfma_f32_16x16x32_bf16 v[70:73], v[158:161], v[208:211], v[70:73]
	v_mfma_f32_16x16x32_bf16 v[70:73], v[168:171], v[212:215], v[70:73]
	v_mfma_f32_16x16x32_bf16 v[110:113], v[172:175], v[184:187], v[110:113]
	v_mfma_f32_16x16x32_bf16 v[110:113], v[176:179], v[188:191], v[110:113]
	v_mfma_f32_16x16x32_bf16 v[94:97], v[172:175], v[192:195], v[94:97]
	v_mfma_f32_16x16x32_bf16 v[94:97], v[176:179], v[196:199], v[94:97]
	v_mfma_f32_16x16x32_bf16 v[78:81], v[172:175], v[200:203], v[78:81]
	v_mfma_f32_16x16x32_bf16 v[78:81], v[176:179], v[204:207], v[78:81]
	v_mfma_f32_16x16x32_bf16 v[66:69], v[172:175], v[208:211], v[66:69]
	v_mfma_f32_16x16x32_bf16 v[66:69], v[176:179], v[212:215], v[66:69]
	s_barrier
	s_add_i32 s60, s50, s38
	v_lshl_add_u64 v[180:181], s[28:29], 0, v[130:131]
	s_mov_b32 m0, s60
	ds_read_b128 v[184:187], v167 offset:16384
	ds_read_b128 v[188:191], v167 offset:17408
	ds_read_b128 v[192:195], v167 offset:18432
	ds_read_b128 v[196:199], v167 offset:19456
	ds_read_b128 v[200:203], v167 offset:20480
	ds_read_b128 v[204:207], v167 offset:21504
	ds_read_b128 v[208:211], v167 offset:22528
	ds_read_b128 v[212:215], v167 offset:23552
	global_load_lds_dwordx4 v[180:181], off
	s_add_i32 m0, s60, 0x2000
	s_add_u32 s60, s28, 0x200000
	v_lshl_add_u64 v[216:217], s[28:29], 0, v[132:133]
	s_addc_u32 s61, s29, 0
	s_add_i32 s62, s51, s38
	global_load_lds_dwordx4 v[216:217], off
	v_lshl_add_u64 v[218:219], s[60:61], 0, v[130:131]
	s_mov_b32 m0, s62
	v_lshl_add_u64 v[220:221], s[30:31], 0, v[132:133]
	global_load_lds_dwordx4 v[218:219], off
	v_lshl_add_u64 v[218:219], s[60:61], 0, v[132:133]
	s_add_i32 m0, s62, 0x2000
	s_nop 0
	global_load_lds_dwordx4 v[218:219], off
	v_lshl_add_u64 v[218:219], s[30:31], 0, v[130:131]
	s_mov_b32 m0, s25
	s_nop 0
	global_load_lds_dwordx4 v[218:219], off
	s_mov_b32 m0, s40
	s_nop 0
	global_load_lds_dwordx4 v[220:221], off
	s_waitcnt vmcnt(8)
	s_waitcnt lgkmcnt(0)
	s_barrier
	s_waitcnt lgkmcnt(0)
	v_mfma_f32_16x16x32_bf16 v[62:65], v[142:145], v[184:187], v[62:65]
	v_mfma_f32_16x16x32_bf16 v[62:65], v[146:149], v[188:191], v[62:65]
	v_mfma_f32_16x16x32_bf16 v[50:53], v[142:145], v[192:195], v[50:53]
	v_mfma_f32_16x16x32_bf16 v[50:53], v[146:149], v[196:199], v[50:53]
	v_mfma_f32_16x16x32_bf16 v[34:37], v[142:145], v[200:203], v[34:37]
	v_mfma_f32_16x16x32_bf16 v[34:37], v[146:149], v[204:207], v[34:37]
	v_mfma_f32_16x16x32_bf16 v[18:21], v[142:145], v[208:211], v[18:21]
	v_mfma_f32_16x16x32_bf16 v[18:21], v[146:149], v[212:215], v[18:21]
	v_mfma_f32_16x16x32_bf16 v[58:61], v[150:153], v[184:187], v[58:61]
	v_mfma_f32_16x16x32_bf16 v[58:61], v[154:157], v[188:191], v[58:61]
	v_mfma_f32_16x16x32_bf16 v[42:45], v[150:153], v[192:195], v[42:45]
	v_mfma_f32_16x16x32_bf16 v[42:45], v[154:157], v[196:199], v[42:45]
	v_mfma_f32_16x16x32_bf16 v[26:29], v[150:153], v[200:203], v[26:29]
	v_mfma_f32_16x16x32_bf16 v[26:29], v[154:157], v[204:207], v[26:29]
	v_mfma_f32_16x16x32_bf16 v[10:13], v[150:153], v[208:211], v[10:13]
	v_mfma_f32_16x16x32_bf16 v[10:13], v[154:157], v[212:215], v[10:13]
	v_mfma_f32_16x16x32_bf16 v[54:57], v[158:161], v[184:187], v[54:57]
	v_mfma_f32_16x16x32_bf16 v[54:57], v[168:171], v[188:191], v[54:57]
	v_mfma_f32_16x16x32_bf16 v[38:41], v[158:161], v[192:195], v[38:41]
	v_mfma_f32_16x16x32_bf16 v[38:41], v[168:171], v[196:199], v[38:41]
	v_mfma_f32_16x16x32_bf16 v[22:25], v[158:161], v[200:203], v[22:25]
	v_mfma_f32_16x16x32_bf16 v[22:25], v[168:171], v[204:207], v[22:25]
	v_mfma_f32_16x16x32_bf16 v[6:9], v[158:161], v[208:211], v[6:9]
	v_mfma_f32_16x16x32_bf16 v[6:9], v[168:171], v[212:215], v[6:9]
	v_mfma_f32_16x16x32_bf16 v[46:49], v[172:175], v[184:187], v[46:49]
	v_mfma_f32_16x16x32_bf16 v[46:49], v[176:179], v[188:191], v[46:49]
	v_mfma_f32_16x16x32_bf16 v[30:33], v[172:175], v[192:195], v[30:33]
	v_mfma_f32_16x16x32_bf16 v[30:33], v[176:179], v[196:199], v[30:33]
	v_mfma_f32_16x16x32_bf16 v[14:17], v[172:175], v[200:203], v[14:17]
	v_mfma_f32_16x16x32_bf16 v[14:17], v[176:179], v[204:207], v[14:17]
	v_mfma_f32_16x16x32_bf16 v[2:5], v[172:175], v[208:211], v[2:5]
	v_mfma_f32_16x16x32_bf16 v[2:5], v[176:179], v[212:215], v[2:5]
	s_barrier
	s_add_i32 s60, 0, 0x18000
	s_add_i32 s61, 0, 0x1c000
	v_add_u32_e32 v154, s60, v162
	v_add_u32_e32 v176, s61, v162
	ds_read_b128 v[142:145], v154
	ds_read_b128 v[146:149], v154 offset:1024
	ds_read_b128 v[150:153], v154 offset:2048
	ds_read_b128 v[154:157], v154 offset:3072
	ds_read_b128 v[158:161], v176
	ds_read_b128 v[168:171], v176 offset:1024
	ds_read_b128 v[172:175], v176 offset:2048
	ds_read_b128 v[176:179], v176 offset:3072
	s_add_u32 s30, s30, 0x200000
	s_addc_u32 s31, s31, 0
	s_mov_b32 m0, s41
	v_lshl_add_u64 v[222:223], s[30:31], 0, v[130:131]
	ds_read_b128 v[184:187], v167 offset:32768
	ds_read_b128 v[188:191], v167 offset:33792
	ds_read_b128 v[192:195], v167 offset:34816
	ds_read_b128 v[196:199], v167 offset:35840
	ds_read_b128 v[200:203], v167 offset:36864
	ds_read_b128 v[204:207], v167 offset:37888
	ds_read_b128 v[208:211], v167 offset:38912
	ds_read_b128 v[212:215], v167 offset:39936
	global_load_lds_dwordx4 v[222:223], off
	v_lshl_add_u64 v[222:223], s[30:31], 0, v[132:133]
	s_mov_b32 m0, s42
	s_nop 0
	global_load_lds_dwordx4 v[222:223], off
	s_waitcnt vmcnt(8)
	s_waitcnt lgkmcnt(0)
	s_barrier
	s_waitcnt lgkmcnt(0)
	v_mfma_f32_16x16x32_bf16 v[126:129], v[142:145], v[184:187], v[126:129]
	v_mfma_f32_16x16x32_bf16 v[126:129], v[146:149], v[188:191], v[126:129]
	v_mfma_f32_16x16x32_bf16 v[114:117], v[142:145], v[192:195], v[114:117]
	v_mfma_f32_16x16x32_bf16 v[114:117], v[146:149], v[196:199], v[114:117]
	v_mfma_f32_16x16x32_bf16 v[98:101], v[142:145], v[200:203], v[98:101]
	v_mfma_f32_16x16x32_bf16 v[98:101], v[146:149], v[204:207], v[98:101]
	v_mfma_f32_16x16x32_bf16 v[82:85], v[142:145], v[208:211], v[82:85]
	v_mfma_f32_16x16x32_bf16 v[82:85], v[146:149], v[212:215], v[82:85]
	v_mfma_f32_16x16x32_bf16 v[122:125], v[150:153], v[184:187], v[122:125]
	v_mfma_f32_16x16x32_bf16 v[122:125], v[154:157], v[188:191], v[122:125]
	v_mfma_f32_16x16x32_bf16 v[106:109], v[150:153], v[192:195], v[106:109]
	v_mfma_f32_16x16x32_bf16 v[106:109], v[154:157], v[196:199], v[106:109]
	v_mfma_f32_16x16x32_bf16 v[90:93], v[150:153], v[200:203], v[90:93]
	v_mfma_f32_16x16x32_bf16 v[90:93], v[154:157], v[204:207], v[90:93]
	v_mfma_f32_16x16x32_bf16 v[74:77], v[150:153], v[208:211], v[74:77]
	v_mfma_f32_16x16x32_bf16 v[74:77], v[154:157], v[212:215], v[74:77]
	v_mfma_f32_16x16x32_bf16 v[118:121], v[158:161], v[184:187], v[118:121]
	v_mfma_f32_16x16x32_bf16 v[118:121], v[168:171], v[188:191], v[118:121]
	v_mfma_f32_16x16x32_bf16 v[102:105], v[158:161], v[192:195], v[102:105]
	v_mfma_f32_16x16x32_bf16 v[102:105], v[168:171], v[196:199], v[102:105]
	v_mfma_f32_16x16x32_bf16 v[86:89], v[158:161], v[200:203], v[86:89]
	v_mfma_f32_16x16x32_bf16 v[86:89], v[168:171], v[204:207], v[86:89]
	v_mfma_f32_16x16x32_bf16 v[70:73], v[158:161], v[208:211], v[70:73]
	v_mfma_f32_16x16x32_bf16 v[70:73], v[168:171], v[212:215], v[70:73]
	v_mfma_f32_16x16x32_bf16 v[110:113], v[172:175], v[184:187], v[110:113]
	v_mfma_f32_16x16x32_bf16 v[110:113], v[176:179], v[188:191], v[110:113]
	v_mfma_f32_16x16x32_bf16 v[94:97], v[172:175], v[192:195], v[94:97]
	v_mfma_f32_16x16x32_bf16 v[94:97], v[176:179], v[196:199], v[94:97]
	v_mfma_f32_16x16x32_bf16 v[78:81], v[172:175], v[200:203], v[78:81]
	v_mfma_f32_16x16x32_bf16 v[78:81], v[176:179], v[204:207], v[78:81]
	v_mfma_f32_16x16x32_bf16 v[66:69], v[172:175], v[208:211], v[66:69]
	v_mfma_f32_16x16x32_bf16 v[66:69], v[176:179], v[212:215], v[66:69]
	s_barrier
	s_add_i32 s30, s60, s38
	v_lshl_add_u64 v[180:181], v[180:181], 0, s[10:11]
	s_mov_b32 m0, s30
	ds_read_b128 v[184:187], v167 offset:49152
	ds_read_b128 v[188:191], v167 offset:50176
	ds_read_b128 v[192:195], v167 offset:51200
	ds_read_b128 v[196:199], v167 offset:52224
	ds_read_b128 v[200:203], v167 offset:53248
	ds_read_b128 v[204:207], v167 offset:54272
	ds_read_b128 v[208:211], v167 offset:55296
	ds_read_b128 v[212:215], v167 offset:56320
	global_load_lds_dwordx4 v[180:181], off
	s_add_i32 m0, s30, 0x2000
	s_add_u32 s28, s28, 0x200080
	v_lshl_add_u64 v[180:181], v[216:217], 0, s[10:11]
	s_addc_u32 s29, s29, 0
	s_add_i32 s30, s61, s38
	global_load_lds_dwordx4 v[180:181], off
	v_lshl_add_u64 v[180:181], s[28:29], 0, v[130:131]
	s_mov_b32 m0, s30
	s_nop 0
	global_load_lds_dwordx4 v[180:181], off
	v_lshl_add_u64 v[180:181], s[28:29], 0, v[132:133]
	s_add_i32 m0, s30, 0x2000
	s_nop 0
	global_load_lds_dwordx4 v[180:181], off
	v_lshl_add_u64 v[180:181], v[218:219], 0, s[10:11]
	s_mov_b32 m0, s45
	s_nop 0
	global_load_lds_dwordx4 v[180:181], off
	v_lshl_add_u64 v[180:181], v[220:221], 0, s[10:11]
	s_mov_b32 m0, s46
	s_nop 0
	global_load_lds_dwordx4 v[180:181], off
	s_waitcnt vmcnt(8)
	s_waitcnt lgkmcnt(0)
	s_barrier
	s_waitcnt lgkmcnt(0)
	v_mfma_f32_16x16x32_bf16 v[62:65], v[142:145], v[184:187], v[62:65]
	v_mfma_f32_16x16x32_bf16 v[62:65], v[146:149], v[188:191], v[62:65]
	v_mfma_f32_16x16x32_bf16 v[50:53], v[142:145], v[192:195], v[50:53]
	v_mfma_f32_16x16x32_bf16 v[50:53], v[146:149], v[196:199], v[50:53]
	v_mfma_f32_16x16x32_bf16 v[34:37], v[142:145], v[200:203], v[34:37]
	v_mfma_f32_16x16x32_bf16 v[34:37], v[146:149], v[204:207], v[34:37]
	v_mfma_f32_16x16x32_bf16 v[18:21], v[142:145], v[208:211], v[18:21]
	v_mfma_f32_16x16x32_bf16 v[18:21], v[146:149], v[212:215], v[18:21]
	v_mfma_f32_16x16x32_bf16 v[58:61], v[150:153], v[184:187], v[58:61]
	v_mfma_f32_16x16x32_bf16 v[58:61], v[154:157], v[188:191], v[58:61]
	v_mfma_f32_16x16x32_bf16 v[42:45], v[150:153], v[192:195], v[42:45]
	v_mfma_f32_16x16x32_bf16 v[42:45], v[154:157], v[196:199], v[42:45]
	v_mfma_f32_16x16x32_bf16 v[26:29], v[150:153], v[200:203], v[26:29]
	v_mfma_f32_16x16x32_bf16 v[26:29], v[154:157], v[204:207], v[26:29]
	v_mfma_f32_16x16x32_bf16 v[10:13], v[150:153], v[208:211], v[10:13]
	v_mfma_f32_16x16x32_bf16 v[10:13], v[154:157], v[212:215], v[10:13]
	v_mfma_f32_16x16x32_bf16 v[54:57], v[158:161], v[184:187], v[54:57]
	v_mfma_f32_16x16x32_bf16 v[54:57], v[168:171], v[188:191], v[54:57]
	v_mfma_f32_16x16x32_bf16 v[38:41], v[158:161], v[192:195], v[38:41]
	v_mfma_f32_16x16x32_bf16 v[38:41], v[168:171], v[196:199], v[38:41]
	v_mfma_f32_16x16x32_bf16 v[22:25], v[158:161], v[200:203], v[22:25]
	v_mfma_f32_16x16x32_bf16 v[22:25], v[168:171], v[204:207], v[22:25]
	v_mfma_f32_16x16x32_bf16 v[6:9], v[158:161], v[208:211], v[6:9]
	v_mfma_f32_16x16x32_bf16 v[6:9], v[168:171], v[212:215], v[6:9]
	v_mfma_f32_16x16x32_bf16 v[46:49], v[172:175], v[184:187], v[46:49]
	v_mfma_f32_16x16x32_bf16 v[46:49], v[176:179], v[188:191], v[46:49]
	v_mfma_f32_16x16x32_bf16 v[30:33], v[172:175], v[192:195], v[30:33]
	v_mfma_f32_16x16x32_bf16 v[30:33], v[176:179], v[196:199], v[30:33]
	v_mfma_f32_16x16x32_bf16 v[14:17], v[172:175], v[200:203], v[14:17]
	v_mfma_f32_16x16x32_bf16 v[14:17], v[176:179], v[204:207], v[14:17]
	v_mfma_f32_16x16x32_bf16 v[2:5], v[172:175], v[208:211], v[2:5]
	v_mfma_f32_16x16x32_bf16 v[2:5], v[176:179], v[212:215], v[2:5]
	s_barrier
	s_add_i32 s59, s59, 2
	s_add_u32 s26, s26, 0x100
	s_addc_u32 s27, s27, 0
	s_add_u32 s57, s57, 0x100
	s_addc_u32 s58, s58, 0
	s_cmpk_gt_u32 s59, 0x7d
	s_cbranch_scc0 .LBB0_763
	s_and_b64 vcc, exec, s[14:15]
	s_cbranch_vccz .LBB0_766
	s_barrier

.LBB0_916:
	ds_read_b128 v[164:167], v158
	ds_read_b128 v[168:171], v158 offset:1024
	ds_read_b128 v[172:175], v158 offset:2048
	ds_read_b128 v[176:179], v158 offset:3072
	ds_read_b128 v[180:183], v159
	ds_read_b128 v[184:187], v159 offset:1024
	ds_read_b128 v[188:191], v159 offset:2048
	ds_read_b128 v[192:195], v159 offset:3072
	s_add_u32 s28, s26, 0xfff00080
	s_addc_u32 s29, s27, -1
	s_cmp_eq_u32 s59, 60
	s_cselect_b32 s31, s19, s29
	s_cselect_b32 s30, s53, s28
	s_cselect_b32 s29, s17, s58
	s_cselect_b32 s28, s56, s57
	v_lshl_add_u64 v[146:147], s[26:27], 0, v[138:139]
	s_add_i32 m0, s25, 0xc000
	ds_read_b128 v[196:199], v160
	ds_read_b128 v[200:203], v160 offset:1024
	ds_read_b128 v[204:207], v160 offset:2048
	ds_read_b128 v[208:211], v160 offset:3072
	ds_read_b128 v[212:215], v160 offset:4096
	ds_read_b128 v[216:219], v160 offset:5120
	ds_read_b128 v[220:223], v160 offset:6144
	ds_read_b128 v[224:227], v160 offset:7168
	global_load_lds_dwordx4 v[146:147], off
	v_lshl_add_u64 v[146:147], s[26:27], 0, v[140:141]
	s_add_i32 m0, s25, 0xe000
	s_nop 0
	global_load_lds_dwordx4 v[146:147], off
	s_waitcnt vmcnt(8)
	s_waitcnt lgkmcnt(0)
	s_barrier
	s_waitcnt lgkmcnt(0)
	v_mfma_f32_16x16x32_bf16 v[126:129], v[164:167], v[196:199], v[126:129]
	v_mfma_f32_16x16x32_bf16 v[126:129], v[168:171], v[200:203], v[126:129]
	v_mfma_f32_16x16x32_bf16 v[110:113], v[164:167], v[204:207], v[110:113]
	v_mfma_f32_16x16x32_bf16 v[110:113], v[168:171], v[208:211], v[110:113]
	v_mfma_f32_16x16x32_bf16 v[94:97], v[164:167], v[212:215], v[94:97]
	v_mfma_f32_16x16x32_bf16 v[94:97], v[168:171], v[216:219], v[94:97]
	v_mfma_f32_16x16x32_bf16 v[78:81], v[164:167], v[220:223], v[78:81]
	v_mfma_f32_16x16x32_bf16 v[78:81], v[168:171], v[224:227], v[78:81]
	v_mfma_f32_16x16x32_bf16 v[122:125], v[172:175], v[196:199], v[122:125]
	v_mfma_f32_16x16x32_bf16 v[122:125], v[176:179], v[200:203], v[122:125]
	v_mfma_f32_16x16x32_bf16 v[106:109], v[172:175], v[204:207], v[106:109]
	v_mfma_f32_16x16x32_bf16 v[106:109], v[176:179], v[208:211], v[106:109]
	v_mfma_f32_16x16x32_bf16 v[90:93], v[172:175], v[212:215], v[90:93]
	v_mfma_f32_16x16x32_bf16 v[90:93], v[176:179], v[216:219], v[90:93]
	v_mfma_f32_16x16x32_bf16 v[74:77], v[172:175], v[220:223], v[74:77]
	v_mfma_f32_16x16x32_bf16 v[74:77], v[176:179], v[224:227], v[74:77]
	v_mfma_f32_16x16x32_bf16 v[118:121], v[180:183], v[196:199], v[118:121]
	v_mfma_f32_16x16x32_bf16 v[118:121], v[184:187], v[200:203], v[118:121]
	v_mfma_f32_16x16x32_bf16 v[102:105], v[180:183], v[204:207], v[102:105]
	v_mfma_f32_16x16x32_bf16 v[102:105], v[184:187], v[208:211], v[102:105]
	v_mfma_f32_16x16x32_bf16 v[86:89], v[180:183], v[212:215], v[86:89]
	v_mfma_f32_16x16x32_bf16 v[86:89], v[184:187], v[216:219], v[86:89]
	v_mfma_f32_16x16x32_bf16 v[70:73], v[180:183], v[220:223], v[70:73]
	v_mfma_f32_16x16x32_bf16 v[70:73], v[184:187], v[224:227], v[70:73]
	v_mfma_f32_16x16x32_bf16 v[114:117], v[188:191], v[196:199], v[114:117]
	v_mfma_f32_16x16x32_bf16 v[114:117], v[192:195], v[200:203], v[114:117]
	v_mfma_f32_16x16x32_bf16 v[98:101], v[188:191], v[204:207], v[98:101]
	v_mfma_f32_16x16x32_bf16 v[98:101], v[192:195], v[208:211], v[98:101]
	v_mfma_f32_16x16x32_bf16 v[82:85], v[188:191], v[212:215], v[82:85]
	v_mfma_f32_16x16x32_bf16 v[82:85], v[192:195], v[216:219], v[82:85]
	v_mfma_f32_16x16x32_bf16 v[66:69], v[188:191], v[220:223], v[66:69]
	v_mfma_f32_16x16x32_bf16 v[66:69], v[192:195], v[224:227], v[66:69]
	s_barrier
	s_add_i32 s60, s45, s38
	v_lshl_add_u64 v[146:147], s[28:29], 0, v[132:133]
	s_mov_b32 m0, s60
	ds_read_b128 v[196:199], v160 offset:16384
	ds_read_b128 v[200:203], v160 offset:17408
	ds_read_b128 v[204:207], v160 offset:18432
	ds_read_b128 v[208:211], v160 offset:19456
	ds_read_b128 v[212:215], v160 offset:20480
	ds_read_b128 v[216:219], v160 offset:21504
	ds_read_b128 v[220:223], v160 offset:22528
	ds_read_b128 v[224:227], v160 offset:23552
	global_load_lds_dwordx4 v[146:147], off
	s_add_i32 m0, s60, 0x2000
	s_add_u32 s60, s28, 0x100000
	v_lshl_add_u64 v[228:229], s[28:29], 0, v[136:137]
	s_addc_u32 s61, s29, 0
	s_add_i32 s62, s46, s38
	global_load_lds_dwordx4 v[228:229], off
	v_lshl_add_u64 v[230:231], s[60:61], 0, v[132:133]
	s_mov_b32 m0, s62
	v_lshl_add_u64 v[232:233], s[30:31], 0, v[134:135]
	global_load_lds_dwordx4 v[230:231], off
	v_lshl_add_u64 v[230:231], s[60:61], 0, v[136:137]
	s_add_i32 m0, s62, 0x2000
	s_nop 0
	global_load_lds_dwordx4 v[230:231], off
	v_lshl_add_u64 v[230:231], s[30:31], 0, v[130:131]
	s_mov_b32 m0, s25
	s_nop 0
	global_load_lds_dwordx4 v[230:231], off
	s_mov_b32 m0, s39
	s_nop 0
	global_load_lds_dwordx4 v[232:233], off
	s_waitcnt vmcnt(8)
	s_waitcnt lgkmcnt(0)
	s_barrier
	s_waitcnt lgkmcnt(0)
	v_mfma_f32_16x16x32_bf16 v[62:65], v[164:167], v[196:199], v[62:65]
	v_mfma_f32_16x16x32_bf16 v[62:65], v[168:171], v[200:203], v[62:65]
	v_mfma_f32_16x16x32_bf16 v[46:49], v[164:167], v[204:207], v[46:49]
	v_mfma_f32_16x16x32_bf16 v[46:49], v[168:171], v[208:211], v[46:49]
	v_mfma_f32_16x16x32_bf16 v[30:33], v[164:167], v[212:215], v[30:33]
	v_mfma_f32_16x16x32_bf16 v[30:33], v[168:171], v[216:219], v[30:33]
	v_mfma_f32_16x16x32_bf16 v[14:17], v[164:167], v[220:223], v[14:17]
	v_mfma_f32_16x16x32_bf16 v[14:17], v[168:171], v[224:227], v[14:17]
	v_mfma_f32_16x16x32_bf16 v[58:61], v[172:175], v[196:199], v[58:61]
	v_mfma_f32_16x16x32_bf16 v[58:61], v[176:179], v[200:203], v[58:61]
	v_mfma_f32_16x16x32_bf16 v[42:45], v[172:175], v[204:207], v[42:45]
	v_mfma_f32_16x16x32_bf16 v[42:45], v[176:179], v[208:211], v[42:45]
	v_mfma_f32_16x16x32_bf16 v[26:29], v[172:175], v[212:215], v[26:29]
	v_mfma_f32_16x16x32_bf16 v[26:29], v[176:179], v[216:219], v[26:29]
	v_mfma_f32_16x16x32_bf16 v[10:13], v[172:175], v[220:223], v[10:13]
	v_mfma_f32_16x16x32_bf16 v[10:13], v[176:179], v[224:227], v[10:13]
	v_mfma_f32_16x16x32_bf16 v[54:57], v[180:183], v[196:199], v[54:57]
	v_mfma_f32_16x16x32_bf16 v[54:57], v[184:187], v[200:203], v[54:57]
	v_mfma_f32_16x16x32_bf16 v[38:41], v[180:183], v[204:207], v[38:41]
	v_mfma_f32_16x16x32_bf16 v[38:41], v[184:187], v[208:211], v[38:41]
	v_mfma_f32_16x16x32_bf16 v[22:25], v[180:183], v[212:215], v[22:25]
	v_mfma_f32_16x16x32_bf16 v[22:25], v[184:187], v[216:219], v[22:25]
	v_mfma_f32_16x16x32_bf16 v[6:9], v[180:183], v[220:223], v[6:9]
	v_mfma_f32_16x16x32_bf16 v[6:9], v[184:187], v[224:227], v[6:9]
	v_mfma_f32_16x16x32_bf16 v[50:53], v[188:191], v[196:199], v[50:53]
	v_mfma_f32_16x16x32_bf16 v[50:53], v[192:195], v[200:203], v[50:53]
	v_mfma_f32_16x16x32_bf16 v[34:37], v[188:191], v[204:207], v[34:37]
	v_mfma_f32_16x16x32_bf16 v[34:37], v[192:195], v[208:211], v[34:37]
	v_mfma_f32_16x16x32_bf16 v[18:21], v[188:191], v[212:215], v[18:21]
	v_mfma_f32_16x16x32_bf16 v[18:21], v[192:195], v[216:219], v[18:21]
	v_mfma_f32_16x16x32_bf16 v[2:5], v[188:191], v[220:223], v[2:5]
	v_mfma_f32_16x16x32_bf16 v[2:5], v[192:195], v[224:227], v[2:5]
	s_barrier
	s_add_i32 s60, 0, 0x18000
	v_add_u32_e32 v161, s60, v156
	s_add_i32 s61, 0, 0x1c000
	ds_read_b128 v[164:167], v161
	ds_read_b128 v[168:171], v161 offset:1024
	ds_read_b128 v[172:175], v161 offset:2048
	ds_read_b128 v[176:179], v161 offset:3072
	v_add_u32_e32 v161, s61, v156
	ds_read_b128 v[180:183], v161
	ds_read_b128 v[184:187], v161 offset:1024
	ds_read_b128 v[188:191], v161 offset:2048
	ds_read_b128 v[192:195], v161 offset:3072
	s_add_u32 s30, s30, 0x100000
	s_addc_u32 s31, s31, 0
	s_mov_b32 m0, s40
	v_lshl_add_u64 v[234:235], s[30:31], 0, v[130:131]
	ds_read_b128 v[196:199], v160 offset:32768
	ds_read_b128 v[200:203], v160 offset:33792
	ds_read_b128 v[204:207], v160 offset:34816
	ds_read_b128 v[208:211], v160 offset:35840
	ds_read_b128 v[212:215], v160 offset:36864
	ds_read_b128 v[216:219], v160 offset:37888
	ds_read_b128 v[220:223], v160 offset:38912
	ds_read_b128 v[224:227], v160 offset:39936
	global_load_lds_dwordx4 v[234:235], off
	v_lshl_add_u64 v[234:235], s[30:31], 0, v[134:135]
	s_mov_b32 m0, s41
	s_nop 0
	global_load_lds_dwordx4 v[234:235], off
	s_waitcnt vmcnt(8)
	s_waitcnt lgkmcnt(0)
	s_barrier
	s_waitcnt lgkmcnt(0)
	v_mfma_f32_16x16x32_bf16 v[126:129], v[164:167], v[196:199], v[126:129]
	v_mfma_f32_16x16x32_bf16 v[126:129], v[168:171], v[200:203], v[126:129]
	v_mfma_f32_16x16x32_bf16 v[110:113], v[164:167], v[204:207], v[110:113]
	v_mfma_f32_16x16x32_bf16 v[110:113], v[168:171], v[208:211], v[110:113]
	v_mfma_f32_16x16x32_bf16 v[94:97], v[164:167], v[212:215], v[94:97]
	v_mfma_f32_16x16x32_bf16 v[94:97], v[168:171], v[216:219], v[94:97]
	v_mfma_f32_16x16x32_bf16 v[78:81], v[164:167], v[220:223], v[78:81]
	v_mfma_f32_16x16x32_bf16 v[78:81], v[168:171], v[224:227], v[78:81]
	v_mfma_f32_16x16x32_bf16 v[122:125], v[172:175], v[196:199], v[122:125]
	v_mfma_f32_16x16x32_bf16 v[122:125], v[176:179], v[200:203], v[122:125]
	v_mfma_f32_16x16x32_bf16 v[106:109], v[172:175], v[204:207], v[106:109]
	v_mfma_f32_16x16x32_bf16 v[106:109], v[176:179], v[208:211], v[106:109]
	v_mfma_f32_16x16x32_bf16 v[90:93], v[172:175], v[212:215], v[90:93]
	v_mfma_f32_16x16x32_bf16 v[90:93], v[176:179], v[216:219], v[90:93]
	v_mfma_f32_16x16x32_bf16 v[74:77], v[172:175], v[220:223], v[74:77]
	v_mfma_f32_16x16x32_bf16 v[74:77], v[176:179], v[224:227], v[74:77]
	v_mfma_f32_16x16x32_bf16 v[118:121], v[180:183], v[196:199], v[118:121]
	v_mfma_f32_16x16x32_bf16 v[118:121], v[184:187], v[200:203], v[118:121]
	v_mfma_f32_16x16x32_bf16 v[102:105], v[180:183], v[204:207], v[102:105]
	v_mfma_f32_16x16x32_bf16 v[102:105], v[184:187], v[208:211], v[102:105]
	v_mfma_f32_16x16x32_bf16 v[86:89], v[180:183], v[212:215], v[86:89]
	v_mfma_f32_16x16x32_bf16 v[86:89], v[184:187], v[216:219], v[86:89]
	v_mfma_f32_16x16x32_bf16 v[70:73], v[180:183], v[220:223], v[70:73]
	v_mfma_f32_16x16x32_bf16 v[70:73], v[184:187], v[224:227], v[70:73]
	v_mfma_f32_16x16x32_bf16 v[114:117], v[188:191], v[196:199], v[114:117]
	v_mfma_f32_16x16x32_bf16 v[114:117], v[192:195], v[200:203], v[114:117]
	v_mfma_f32_16x16x32_bf16 v[98:101], v[188:191], v[204:207], v[98:101]
	v_mfma_f32_16x16x32_bf16 v[98:101], v[192:195], v[208:211], v[98:101]
	v_mfma_f32_16x16x32_bf16 v[82:85], v[188:191], v[212:215], v[82:85]
	v_mfma_f32_16x16x32_bf16 v[82:85], v[192:195], v[216:219], v[82:85]
	v_mfma_f32_16x16x32_bf16 v[66:69], v[188:191], v[220:223], v[66:69]
	v_mfma_f32_16x16x32_bf16 v[66:69], v[192:195], v[224:227], v[66:69]
	s_barrier
	s_add_i32 s30, s60, s38
	v_lshl_add_u64 v[146:147], v[146:147], 0, s[12:13]
	s_mov_b32 m0, s30
	ds_read_b128 v[196:199], v160 offset:49152
	ds_read_b128 v[200:203], v160 offset:50176
	ds_read_b128 v[204:207], v160 offset:51200
	ds_read_b128 v[208:211], v160 offset:52224
	ds_read_b128 v[212:215], v160 offset:53248
	ds_read_b128 v[216:219], v160 offset:54272
	ds_read_b128 v[220:223], v160 offset:55296
	ds_read_b128 v[224:227], v160 offset:56320
	global_load_lds_dwordx4 v[146:147], off
	s_add_i32 m0, s30, 0x2000
	s_add_u32 s28, s28, 0x100080
	v_lshl_add_u64 v[146:147], v[228:229], 0, s[12:13]
	s_addc_u32 s29, s29, 0
	s_add_i32 s30, s61, s38
	global_load_lds_dwordx4 v[146:147], off
	v_lshl_add_u64 v[146:147], s[28:29], 0, v[132:133]
	s_mov_b32 m0, s30
	s_nop 0
	global_load_lds_dwordx4 v[146:147], off
	v_lshl_add_u64 v[146:147], s[28:29], 0, v[136:137]
	s_add_i32 m0, s30, 0x2000
	s_nop 0
	global_load_lds_dwordx4 v[146:147], off
	v_lshl_add_u64 v[146:147], v[230:231], 0, s[12:13]
	s_mov_b32 m0, s42
	s_nop 0
	global_load_lds_dwordx4 v[146:147], off
	v_lshl_add_u64 v[146:147], v[232:233], 0, s[12:13]
	s_mov_b32 m0, s43
	s_nop 0
	global_load_lds_dwordx4 v[146:147], off
	s_waitcnt vmcnt(8)
	s_waitcnt lgkmcnt(0)
	s_barrier
	s_waitcnt lgkmcnt(0)
	v_mfma_f32_16x16x32_bf16 v[62:65], v[164:167], v[196:199], v[62:65]
	v_mfma_f32_16x16x32_bf16 v[62:65], v[168:171], v[200:203], v[62:65]
	v_mfma_f32_16x16x32_bf16 v[46:49], v[164:167], v[204:207], v[46:49]
	v_mfma_f32_16x16x32_bf16 v[46:49], v[168:171], v[208:211], v[46:49]
	v_mfma_f32_16x16x32_bf16 v[30:33], v[164:167], v[212:215], v[30:33]
	v_mfma_f32_16x16x32_bf16 v[30:33], v[168:171], v[216:219], v[30:33]
	v_mfma_f32_16x16x32_bf16 v[14:17], v[164:167], v[220:223], v[14:17]
	v_mfma_f32_16x16x32_bf16 v[14:17], v[168:171], v[224:227], v[14:17]
	v_mfma_f32_16x16x32_bf16 v[58:61], v[172:175], v[196:199], v[58:61]
	v_mfma_f32_16x16x32_bf16 v[58:61], v[176:179], v[200:203], v[58:61]
	v_mfma_f32_16x16x32_bf16 v[42:45], v[172:175], v[204:207], v[42:45]
	v_mfma_f32_16x16x32_bf16 v[42:45], v[176:179], v[208:211], v[42:45]
	v_mfma_f32_16x16x32_bf16 v[26:29], v[172:175], v[212:215], v[26:29]
	v_mfma_f32_16x16x32_bf16 v[26:29], v[176:179], v[216:219], v[26:29]
	v_mfma_f32_16x16x32_bf16 v[10:13], v[172:175], v[220:223], v[10:13]
	v_mfma_f32_16x16x32_bf16 v[10:13], v[176:179], v[224:227], v[10:13]
	v_mfma_f32_16x16x32_bf16 v[54:57], v[180:183], v[196:199], v[54:57]
	v_mfma_f32_16x16x32_bf16 v[54:57], v[184:187], v[200:203], v[54:57]
	v_mfma_f32_16x16x32_bf16 v[38:41], v[180:183], v[204:207], v[38:41]
	v_mfma_f32_16x16x32_bf16 v[38:41], v[184:187], v[208:211], v[38:41]
	v_mfma_f32_16x16x32_bf16 v[22:25], v[180:183], v[212:215], v[22:25]
	v_mfma_f32_16x16x32_bf16 v[22:25], v[184:187], v[216:219], v[22:25]
	v_mfma_f32_16x16x32_bf16 v[6:9], v[180:183], v[220:223], v[6:9]
	v_mfma_f32_16x16x32_bf16 v[6:9], v[184:187], v[224:227], v[6:9]
	v_mfma_f32_16x16x32_bf16 v[50:53], v[188:191], v[196:199], v[50:53]
	v_mfma_f32_16x16x32_bf16 v[50:53], v[192:195], v[200:203], v[50:53]
	v_mfma_f32_16x16x32_bf16 v[34:37], v[188:191], v[204:207], v[34:37]
	v_mfma_f32_16x16x32_bf16 v[34:37], v[192:195], v[208:211], v[34:37]
	v_mfma_f32_16x16x32_bf16 v[18:21], v[188:191], v[212:215], v[18:21]
	v_mfma_f32_16x16x32_bf16 v[18:21], v[192:195], v[216:219], v[18:21]
	v_mfma_f32_16x16x32_bf16 v[2:5], v[188:191], v[220:223], v[2:5]
	v_mfma_f32_16x16x32_bf16 v[2:5], v[192:195], v[224:227], v[2:5]
	s_barrier
	s_add_i32 s59, s59, 2
	s_add_u32 s26, s26, 0x100
	s_addc_u32 s27, s27, 0
	s_add_u32 s57, s57, 0x100
	s_addc_u32 s58, s58, 0
	s_cmp_gt_u32 s59, 61
	s_cbranch_scc0 .LBB0_916
	s_and_b64 vcc, exec, s[14:15]
	s_cbranch_vccz .LBB0_919
	s_barrier

.LBB0_948:
	v_add_u32_e32 v147, s63, v161
	ds_read_b128 v[168:171], v147
	ds_read_b128 v[172:175], v147 offset:1024
	ds_read_b128 v[176:179], v147 offset:2048
	ds_read_b128 v[180:183], v147 offset:3072
	v_add_u32_e32 v147, s64, v161
	ds_read_b128 v[184:187], v147
	ds_read_b128 v[188:191], v147 offset:1024
	ds_read_b128 v[192:195], v147 offset:2048
	ds_read_b128 v[196:199], v147 offset:3072
	s_cmp_eq_u32 s46, 60
	v_lshl_add_u64 v[200:201], v[156:157], 0, s[34:35]
	s_cselect_b64 vcc, -1, 0
	v_cndmask_b32_e32 v233, v201, v1, vcc
	v_cndmask_b32_e32 v232, v200, v152, vcc
	v_cndmask_b32_e32 v235, v159, v145, vcc
	v_cndmask_b32_e32 v234, v158, v154, vcc
	v_lshl_add_u64 v[236:237], v[156:157], 0, v[138:139]
	s_add_i32 m0, s56, 0xc000
	ds_read_b128 v[200:203], v164
	ds_read_b128 v[204:207], v164 offset:1024
	ds_read_b128 v[208:211], v164 offset:2048
	ds_read_b128 v[212:215], v164 offset:3072
	ds_read_b128 v[216:219], v164 offset:4096
	ds_read_b128 v[220:223], v164 offset:5120
	ds_read_b128 v[224:227], v164 offset:6144
	ds_read_b128 v[228:231], v164 offset:7168
	global_load_lds_dwordx4 v[236:237], off
	v_lshl_add_u64 v[236:237], v[156:157], 0, v[140:141]
	s_add_i32 m0, s56, 0xe000
	s_nop 0
	global_load_lds_dwordx4 v[236:237], off
	s_waitcnt vmcnt(8)
	s_waitcnt lgkmcnt(0)
	s_barrier
	s_waitcnt lgkmcnt(0)
	v_mfma_f32_16x16x32_bf16 v[126:129], v[168:171], v[200:203], v[126:129]
	v_mfma_f32_16x16x32_bf16 v[126:129], v[172:175], v[204:207], v[126:129]
	v_mfma_f32_16x16x32_bf16 v[110:113], v[168:171], v[208:211], v[110:113]
	v_mfma_f32_16x16x32_bf16 v[110:113], v[172:175], v[212:215], v[110:113]
	v_mfma_f32_16x16x32_bf16 v[94:97], v[168:171], v[216:219], v[94:97]
	v_mfma_f32_16x16x32_bf16 v[94:97], v[172:175], v[220:223], v[94:97]
	v_mfma_f32_16x16x32_bf16 v[78:81], v[168:171], v[224:227], v[78:81]
	v_mfma_f32_16x16x32_bf16 v[78:81], v[172:175], v[228:231], v[78:81]
	v_mfma_f32_16x16x32_bf16 v[122:125], v[176:179], v[200:203], v[122:125]
	v_mfma_f32_16x16x32_bf16 v[122:125], v[180:183], v[204:207], v[122:125]
	v_mfma_f32_16x16x32_bf16 v[106:109], v[176:179], v[208:211], v[106:109]
	v_mfma_f32_16x16x32_bf16 v[106:109], v[180:183], v[212:215], v[106:109]
	v_mfma_f32_16x16x32_bf16 v[90:93], v[176:179], v[216:219], v[90:93]
	v_mfma_f32_16x16x32_bf16 v[90:93], v[180:183], v[220:223], v[90:93]
	v_mfma_f32_16x16x32_bf16 v[74:77], v[176:179], v[224:227], v[74:77]
	v_mfma_f32_16x16x32_bf16 v[74:77], v[180:183], v[228:231], v[74:77]
	v_mfma_f32_16x16x32_bf16 v[118:121], v[184:187], v[200:203], v[118:121]
	v_mfma_f32_16x16x32_bf16 v[118:121], v[188:191], v[204:207], v[118:121]
	v_mfma_f32_16x16x32_bf16 v[102:105], v[184:187], v[208:211], v[102:105]
	v_mfma_f32_16x16x32_bf16 v[102:105], v[188:191], v[212:215], v[102:105]
	v_mfma_f32_16x16x32_bf16 v[86:89], v[184:187], v[216:219], v[86:89]
	v_mfma_f32_16x16x32_bf16 v[86:89], v[188:191], v[220:223], v[86:89]
	v_mfma_f32_16x16x32_bf16 v[70:73], v[184:187], v[224:227], v[70:73]
	v_mfma_f32_16x16x32_bf16 v[70:73], v[188:191], v[228:231], v[70:73]
	v_mfma_f32_16x16x32_bf16 v[114:117], v[192:195], v[200:203], v[114:117]
	v_mfma_f32_16x16x32_bf16 v[114:117], v[196:199], v[204:207], v[114:117]
	v_mfma_f32_16x16x32_bf16 v[98:101], v[192:195], v[208:211], v[98:101]
	v_mfma_f32_16x16x32_bf16 v[98:101], v[196:199], v[212:215], v[98:101]
	v_mfma_f32_16x16x32_bf16 v[82:85], v[192:195], v[216:219], v[82:85]
	v_mfma_f32_16x16x32_bf16 v[82:85], v[196:199], v[220:223], v[82:85]
	v_mfma_f32_16x16x32_bf16 v[66:69], v[192:195], v[224:227], v[66:69]
	v_mfma_f32_16x16x32_bf16 v[66:69], v[196:199], v[228:231], v[66:69]
	s_barrier
	s_add_i32 s47, s63, s53
	v_lshl_add_u64 v[236:237], v[234:235], 0, v[132:133]
	s_mov_b32 m0, s47
	ds_read_b128 v[200:203], v164 offset:16384
	ds_read_b128 v[204:207], v164 offset:17408
	ds_read_b128 v[208:211], v164 offset:18432
	ds_read_b128 v[212:215], v164 offset:19456
	ds_read_b128 v[216:219], v164 offset:20480
	ds_read_b128 v[220:223], v164 offset:21504
	ds_read_b128 v[224:227], v164 offset:22528
	ds_read_b128 v[228:231], v164 offset:23552
	global_load_lds_dwordx4 v[236:237], off
	v_lshl_add_u64 v[238:239], v[234:235], 0, v[136:137]
	s_add_i32 m0, s47, 0x2000
	v_lshl_add_u64 v[240:241], v[234:235], 0, s[10:11]
	s_add_i32 s47, s64, s53
	global_load_lds_dwordx4 v[238:239], off
	v_lshl_add_u64 v[242:243], v[240:241], 0, v[132:133]
	s_mov_b32 m0, s47
	v_lshl_add_u64 v[240:241], v[240:241], 0, v[136:137]
	global_load_lds_dwordx4 v[242:243], off
	s_add_i32 m0, s47, 0x2000
	v_lshl_add_u64 v[242:243], v[232:233], 0, v[134:135]
	global_load_lds_dwordx4 v[240:241], off
	v_lshl_add_u64 v[240:241], v[232:233], 0, v[130:131]
	s_mov_b32 m0, s56
	s_nop 0
	global_load_lds_dwordx4 v[240:241], off
	s_mov_b32 m0, s57
	s_nop 0
	global_load_lds_dwordx4 v[242:243], off
	s_waitcnt vmcnt(8)
	s_waitcnt lgkmcnt(0)
	s_barrier
	s_waitcnt lgkmcnt(0)
	v_mfma_f32_16x16x32_bf16 v[62:65], v[168:171], v[200:203], v[62:65]
	v_mfma_f32_16x16x32_bf16 v[62:65], v[172:175], v[204:207], v[62:65]
	v_mfma_f32_16x16x32_bf16 v[46:49], v[168:171], v[208:211], v[46:49]
	v_mfma_f32_16x16x32_bf16 v[46:49], v[172:175], v[212:215], v[46:49]
	v_mfma_f32_16x16x32_bf16 v[30:33], v[168:171], v[216:219], v[30:33]
	v_mfma_f32_16x16x32_bf16 v[30:33], v[172:175], v[220:223], v[30:33]
	v_mfma_f32_16x16x32_bf16 v[14:17], v[168:171], v[224:227], v[14:17]
	v_mfma_f32_16x16x32_bf16 v[14:17], v[172:175], v[228:231], v[14:17]
	v_mfma_f32_16x16x32_bf16 v[58:61], v[176:179], v[200:203], v[58:61]
	v_mfma_f32_16x16x32_bf16 v[58:61], v[180:183], v[204:207], v[58:61]
	v_mfma_f32_16x16x32_bf16 v[42:45], v[176:179], v[208:211], v[42:45]
	v_mfma_f32_16x16x32_bf16 v[42:45], v[180:183], v[212:215], v[42:45]
	v_mfma_f32_16x16x32_bf16 v[26:29], v[176:179], v[216:219], v[26:29]
	v_mfma_f32_16x16x32_bf16 v[26:29], v[180:183], v[220:223], v[26:29]
	v_mfma_f32_16x16x32_bf16 v[10:13], v[176:179], v[224:227], v[10:13]
	v_mfma_f32_16x16x32_bf16 v[10:13], v[180:183], v[228:231], v[10:13]
	v_mfma_f32_16x16x32_bf16 v[54:57], v[184:187], v[200:203], v[54:57]
	v_mfma_f32_16x16x32_bf16 v[54:57], v[188:191], v[204:207], v[54:57]
	v_mfma_f32_16x16x32_bf16 v[38:41], v[184:187], v[208:211], v[38:41]
	v_mfma_f32_16x16x32_bf16 v[38:41], v[188:191], v[212:215], v[38:41]
	v_mfma_f32_16x16x32_bf16 v[22:25], v[184:187], v[216:219], v[22:25]
	v_mfma_f32_16x16x32_bf16 v[22:25], v[188:191], v[220:223], v[22:25]
	v_mfma_f32_16x16x32_bf16 v[6:9], v[184:187], v[224:227], v[6:9]
	v_mfma_f32_16x16x32_bf16 v[6:9], v[188:191], v[228:231], v[6:9]
	v_mfma_f32_16x16x32_bf16 v[50:53], v[192:195], v[200:203], v[50:53]
	v_mfma_f32_16x16x32_bf16 v[50:53], v[196:199], v[204:207], v[50:53]
	v_mfma_f32_16x16x32_bf16 v[34:37], v[192:195], v[208:211], v[34:37]
	v_mfma_f32_16x16x32_bf16 v[34:37], v[196:199], v[212:215], v[34:37]
	v_mfma_f32_16x16x32_bf16 v[18:21], v[192:195], v[216:219], v[18:21]
	v_mfma_f32_16x16x32_bf16 v[18:21], v[196:199], v[220:223], v[18:21]
	v_mfma_f32_16x16x32_bf16 v[2:5], v[192:195], v[224:227], v[2:5]
	v_mfma_f32_16x16x32_bf16 v[2:5], v[196:199], v[228:231], v[2:5]
	s_barrier
	s_add_i32 s47, 0, 0x18000
	v_add_u32_e32 v147, s47, v161
	s_add_i32 s48, 0, 0x1c000
	ds_read_b128 v[168:171], v147
	ds_read_b128 v[172:175], v147 offset:1024
	ds_read_b128 v[176:179], v147 offset:2048
	ds_read_b128 v[180:183], v147 offset:3072
	v_add_u32_e32 v147, s48, v161
	ds_read_b128 v[184:187], v147
	ds_read_b128 v[188:191], v147 offset:1024
	ds_read_b128 v[192:195], v147 offset:2048
	ds_read_b128 v[196:199], v147 offset:3072
	v_lshl_add_u64 v[232:233], v[232:233], 0, s[10:11]
	s_mov_b32 m0, s58
	v_lshl_add_u64 v[244:245], v[232:233], 0, v[130:131]
	ds_read_b128 v[200:203], v164 offset:32768
	ds_read_b128 v[204:207], v164 offset:33792
	ds_read_b128 v[208:211], v164 offset:34816
	ds_read_b128 v[212:215], v164 offset:35840
	ds_read_b128 v[216:219], v164 offset:36864
	ds_read_b128 v[220:223], v164 offset:37888
	ds_read_b128 v[224:227], v164 offset:38912
	ds_read_b128 v[228:231], v164 offset:39936
	global_load_lds_dwordx4 v[244:245], off
	v_lshl_add_u64 v[232:233], v[232:233], 0, v[134:135]
	s_mov_b32 m0, s59
	s_nop 0
	global_load_lds_dwordx4 v[232:233], off
	s_waitcnt vmcnt(8)
	s_waitcnt lgkmcnt(0)
	s_barrier
	s_waitcnt lgkmcnt(0)
	v_mfma_f32_16x16x32_bf16 v[126:129], v[168:171], v[200:203], v[126:129]
	v_mfma_f32_16x16x32_bf16 v[126:129], v[172:175], v[204:207], v[126:129]
	v_mfma_f32_16x16x32_bf16 v[110:113], v[168:171], v[208:211], v[110:113]
	v_mfma_f32_16x16x32_bf16 v[110:113], v[172:175], v[212:215], v[110:113]
	v_mfma_f32_16x16x32_bf16 v[94:97], v[168:171], v[216:219], v[94:97]
	v_mfma_f32_16x16x32_bf16 v[94:97], v[172:175], v[220:223], v[94:97]
	v_mfma_f32_16x16x32_bf16 v[78:81], v[168:171], v[224:227], v[78:81]
	v_mfma_f32_16x16x32_bf16 v[78:81], v[172:175], v[228:231], v[78:81]
	v_mfma_f32_16x16x32_bf16 v[122:125], v[176:179], v[200:203], v[122:125]
	v_mfma_f32_16x16x32_bf16 v[122:125], v[180:183], v[204:207], v[122:125]
	v_mfma_f32_16x16x32_bf16 v[106:109], v[176:179], v[208:211], v[106:109]
	v_mfma_f32_16x16x32_bf16 v[106:109], v[180:183], v[212:215], v[106:109]
	v_mfma_f32_16x16x32_bf16 v[90:93], v[176:179], v[216:219], v[90:93]
	v_mfma_f32_16x16x32_bf16 v[90:93], v[180:183], v[220:223], v[90:93]
	v_mfma_f32_16x16x32_bf16 v[74:77], v[176:179], v[224:227], v[74:77]
	v_mfma_f32_16x16x32_bf16 v[74:77], v[180:183], v[228:231], v[74:77]
	v_mfma_f32_16x16x32_bf16 v[118:121], v[184:187], v[200:203], v[118:121]
	v_mfma_f32_16x16x32_bf16 v[118:121], v[188:191], v[204:207], v[118:121]
	v_mfma_f32_16x16x32_bf16 v[102:105], v[184:187], v[208:211], v[102:105]
	v_mfma_f32_16x16x32_bf16 v[102:105], v[188:191], v[212:215], v[102:105]
	v_mfma_f32_16x16x32_bf16 v[86:89], v[184:187], v[216:219], v[86:89]
	v_mfma_f32_16x16x32_bf16 v[86:89], v[188:191], v[220:223], v[86:89]
	v_mfma_f32_16x16x32_bf16 v[70:73], v[184:187], v[224:227], v[70:73]
	v_mfma_f32_16x16x32_bf16 v[70:73], v[188:191], v[228:231], v[70:73]
	v_mfma_f32_16x16x32_bf16 v[114:117], v[192:195], v[200:203], v[114:117]
	v_mfma_f32_16x16x32_bf16 v[114:117], v[196:199], v[204:207], v[114:117]
	v_mfma_f32_16x16x32_bf16 v[98:101], v[192:195], v[208:211], v[98:101]
	v_mfma_f32_16x16x32_bf16 v[98:101], v[196:199], v[212:215], v[98:101]
	v_mfma_f32_16x16x32_bf16 v[82:85], v[192:195], v[216:219], v[82:85]
	v_mfma_f32_16x16x32_bf16 v[82:85], v[196:199], v[220:223], v[82:85]
	v_mfma_f32_16x16x32_bf16 v[66:69], v[192:195], v[224:227], v[66:69]
	v_mfma_f32_16x16x32_bf16 v[66:69], v[196:199], v[228:231], v[66:69]
	s_barrier
	s_add_i32 s47, s47, s53
	v_lshl_add_u64 v[232:233], v[236:237], 0, s[18:19]
	s_mov_b32 m0, s47
	ds_read_b128 v[200:203], v164 offset:49152
	ds_read_b128 v[204:207], v164 offset:50176
	ds_read_b128 v[208:211], v164 offset:51200
	ds_read_b128 v[212:215], v164 offset:52224
	ds_read_b128 v[216:219], v164 offset:53248
	ds_read_b128 v[220:223], v164 offset:54272
	ds_read_b128 v[224:227], v164 offset:55296
	ds_read_b128 v[228:231], v164 offset:56320
	global_load_lds_dwordx4 v[232:233], off
	v_lshl_add_u64 v[232:233], v[238:239], 0, s[18:19]
	s_add_i32 m0, s47, 0x2000
	s_add_i32 s47, s48, s53
	global_load_lds_dwordx4 v[232:233], off
	v_lshl_add_u64 v[232:233], v[234:235], 0, s[22:23]
	v_lshl_add_u64 v[234:235], v[232:233], 0, v[132:133]
	s_mov_b32 m0, s47
	v_lshl_add_u64 v[232:233], v[232:233], 0, v[136:137]
	global_load_lds_dwordx4 v[234:235], off
	s_add_i32 m0, s47, 0x2000
	s_nop 0
	global_load_lds_dwordx4 v[232:233], off
	v_lshl_add_u64 v[232:233], v[240:241], 0, s[18:19]
	s_mov_b32 m0, s61
	s_nop 0
	global_load_lds_dwordx4 v[232:233], off
	v_lshl_add_u64 v[232:233], v[242:243], 0, s[18:19]
	s_mov_b32 m0, s62
	s_nop 0
	global_load_lds_dwordx4 v[232:233], off
	s_waitcnt vmcnt(8)
	s_waitcnt lgkmcnt(0)
	s_barrier
	s_waitcnt lgkmcnt(0)
	v_mfma_f32_16x16x32_bf16 v[62:65], v[168:171], v[200:203], v[62:65]
	v_mfma_f32_16x16x32_bf16 v[62:65], v[172:175], v[204:207], v[62:65]
	v_mfma_f32_16x16x32_bf16 v[46:49], v[168:171], v[208:211], v[46:49]
	v_mfma_f32_16x16x32_bf16 v[46:49], v[172:175], v[212:215], v[46:49]
	v_mfma_f32_16x16x32_bf16 v[30:33], v[168:171], v[216:219], v[30:33]
	v_mfma_f32_16x16x32_bf16 v[30:33], v[172:175], v[220:223], v[30:33]
	v_mfma_f32_16x16x32_bf16 v[14:17], v[168:171], v[224:227], v[14:17]
	v_mfma_f32_16x16x32_bf16 v[14:17], v[172:175], v[228:231], v[14:17]
	v_mfma_f32_16x16x32_bf16 v[58:61], v[176:179], v[200:203], v[58:61]
	v_mfma_f32_16x16x32_bf16 v[58:61], v[180:183], v[204:207], v[58:61]
	v_mfma_f32_16x16x32_bf16 v[42:45], v[176:179], v[208:211], v[42:45]
	v_mfma_f32_16x16x32_bf16 v[42:45], v[180:183], v[212:215], v[42:45]
	v_mfma_f32_16x16x32_bf16 v[26:29], v[176:179], v[216:219], v[26:29]
	v_mfma_f32_16x16x32_bf16 v[26:29], v[180:183], v[220:223], v[26:29]
	v_mfma_f32_16x16x32_bf16 v[10:13], v[176:179], v[224:227], v[10:13]
	v_mfma_f32_16x16x32_bf16 v[10:13], v[180:183], v[228:231], v[10:13]
	v_mfma_f32_16x16x32_bf16 v[54:57], v[184:187], v[200:203], v[54:57]
	v_mfma_f32_16x16x32_bf16 v[54:57], v[188:191], v[204:207], v[54:57]
	v_mfma_f32_16x16x32_bf16 v[38:41], v[184:187], v[208:211], v[38:41]
	v_mfma_f32_16x16x32_bf16 v[38:41], v[188:191], v[212:215], v[38:41]
	v_mfma_f32_16x16x32_bf16 v[22:25], v[184:187], v[216:219], v[22:25]
	v_mfma_f32_16x16x32_bf16 v[22:25], v[188:191], v[220:223], v[22:25]
	v_mfma_f32_16x16x32_bf16 v[6:9], v[184:187], v[224:227], v[6:9]
	v_mfma_f32_16x16x32_bf16 v[6:9], v[188:191], v[228:231], v[6:9]
	v_mfma_f32_16x16x32_bf16 v[50:53], v[192:195], v[200:203], v[50:53]
	v_mfma_f32_16x16x32_bf16 v[50:53], v[196:199], v[204:207], v[50:53]
	v_mfma_f32_16x16x32_bf16 v[34:37], v[192:195], v[208:211], v[34:37]
	v_mfma_f32_16x16x32_bf16 v[34:37], v[196:199], v[212:215], v[34:37]
	v_mfma_f32_16x16x32_bf16 v[18:21], v[192:195], v[216:219], v[18:21]
	v_mfma_f32_16x16x32_bf16 v[18:21], v[196:199], v[220:223], v[18:21]
	v_mfma_f32_16x16x32_bf16 v[2:5], v[192:195], v[224:227], v[2:5]
	v_mfma_f32_16x16x32_bf16 v[2:5], v[196:199], v[228:231], v[2:5]
	s_barrier
	s_add_i32 s46, s46, 2
	v_lshl_add_u64 v[156:157], v[156:157], 0, s[30:31]
	s_cmp_gt_u32 s46, 61
	v_lshl_add_u64 v[158:159], v[158:159], 0, s[30:31]
	s_cbranch_scc0 .LBB0_948
	s_and_b64 vcc, exec, s[24:25]
	s_cbranch_vccz .LBB0_951
	s_barrier

.LBB0_1098:
	ds_read_b128 v[140:143], v165
	ds_read_b128 v[144:147], v165 offset:1024
	ds_read_b128 v[148:151], v165 offset:2048
	ds_read_b128 v[152:155], v165 offset:3072
	ds_read_b128 v[156:159], v166
	ds_read_b128 v[168:171], v166 offset:1024
	ds_read_b128 v[172:175], v166 offset:2048
	ds_read_b128 v[176:179], v166 offset:3072
	s_add_u32 s28, s26, 0xffe00080
	s_addc_u32 s29, s27, -1
	s_cmpk_eq_i32 s55, 0x7c
	s_cselect_b32 s31, s19, s29
	s_cselect_b32 s30, s51, s28
	s_cselect_b32 s29, s17, s54
	s_cselect_b32 s28, s52, s53
	v_lshl_add_u64 v[160:161], s[26:27], 0, v[132:133]
	s_add_i32 m0, s25, 0xc000
	ds_read_b128 v[180:183], v167
	ds_read_b128 v[184:187], v167 offset:1024
	ds_read_b128 v[188:191], v167 offset:2048
	ds_read_b128 v[192:195], v167 offset:3072
	ds_read_b128 v[196:199], v167 offset:4096
	ds_read_b128 v[200:203], v167 offset:5120
	ds_read_b128 v[204:207], v167 offset:6144
	ds_read_b128 v[208:211], v167 offset:7168
	global_load_lds_dwordx4 v[160:161], off
	v_lshl_add_u64 v[160:161], s[26:27], 0, v[134:135]
	s_add_i32 m0, s25, 0xe000
	s_nop 0
	global_load_lds_dwordx4 v[160:161], off
	s_waitcnt vmcnt(8)
	s_waitcnt lgkmcnt(0)
	s_barrier
	s_waitcnt lgkmcnt(0)
	v_mfma_f32_16x16x32_bf16 v[124:127], v[140:143], v[180:183], v[124:127]
	v_mfma_f32_16x16x32_bf16 v[124:127], v[144:147], v[184:187], v[124:127]
	v_mfma_f32_16x16x32_bf16 v[108:111], v[140:143], v[188:191], v[108:111]
	v_mfma_f32_16x16x32_bf16 v[108:111], v[144:147], v[192:195], v[108:111]
	v_mfma_f32_16x16x32_bf16 v[92:95], v[140:143], v[196:199], v[92:95]
	v_mfma_f32_16x16x32_bf16 v[92:95], v[144:147], v[200:203], v[92:95]
	v_mfma_f32_16x16x32_bf16 v[76:79], v[140:143], v[204:207], v[76:79]
	v_mfma_f32_16x16x32_bf16 v[76:79], v[144:147], v[208:211], v[76:79]
	v_mfma_f32_16x16x32_bf16 v[120:123], v[148:151], v[180:183], v[120:123]
	v_mfma_f32_16x16x32_bf16 v[120:123], v[152:155], v[184:187], v[120:123]
	v_mfma_f32_16x16x32_bf16 v[104:107], v[148:151], v[188:191], v[104:107]
	v_mfma_f32_16x16x32_bf16 v[104:107], v[152:155], v[192:195], v[104:107]
	v_mfma_f32_16x16x32_bf16 v[88:91], v[148:151], v[196:199], v[88:91]
	v_mfma_f32_16x16x32_bf16 v[88:91], v[152:155], v[200:203], v[88:91]
	v_mfma_f32_16x16x32_bf16 v[72:75], v[148:151], v[204:207], v[72:75]
	v_mfma_f32_16x16x32_bf16 v[72:75], v[152:155], v[208:211], v[72:75]
	v_mfma_f32_16x16x32_bf16 v[116:119], v[156:159], v[180:183], v[116:119]
	v_mfma_f32_16x16x32_bf16 v[116:119], v[168:171], v[184:187], v[116:119]
	v_mfma_f32_16x16x32_bf16 v[100:103], v[156:159], v[188:191], v[100:103]
	v_mfma_f32_16x16x32_bf16 v[100:103], v[168:171], v[192:195], v[100:103]
	v_mfma_f32_16x16x32_bf16 v[84:87], v[156:159], v[196:199], v[84:87]
	v_mfma_f32_16x16x32_bf16 v[84:87], v[168:171], v[200:203], v[84:87]
	v_mfma_f32_16x16x32_bf16 v[68:71], v[156:159], v[204:207], v[68:71]
	v_mfma_f32_16x16x32_bf16 v[68:71], v[168:171], v[208:211], v[68:71]
	v_mfma_f32_16x16x32_bf16 v[112:115], v[172:175], v[180:183], v[112:115]
	v_mfma_f32_16x16x32_bf16 v[112:115], v[176:179], v[184:187], v[112:115]
	v_mfma_f32_16x16x32_bf16 v[96:99], v[172:175], v[188:191], v[96:99]
	v_mfma_f32_16x16x32_bf16 v[96:99], v[176:179], v[192:195], v[96:99]
	v_mfma_f32_16x16x32_bf16 v[80:83], v[172:175], v[196:199], v[80:83]
	v_mfma_f32_16x16x32_bf16 v[80:83], v[176:179], v[200:203], v[80:83]
	v_mfma_f32_16x16x32_bf16 v[64:67], v[172:175], v[204:207], v[64:67]
	v_mfma_f32_16x16x32_bf16 v[64:67], v[176:179], v[208:211], v[64:67]
	s_barrier
	s_add_i32 s56, s48, s38
	v_lshl_add_u64 v[160:161], s[28:29], 0, v[128:129]
	s_mov_b32 m0, s56
	ds_read_b128 v[180:183], v167 offset:16384
	ds_read_b128 v[184:187], v167 offset:17408
	ds_read_b128 v[188:191], v167 offset:18432
	ds_read_b128 v[192:195], v167 offset:19456
	ds_read_b128 v[196:199], v167 offset:20480
	ds_read_b128 v[200:203], v167 offset:21504
	ds_read_b128 v[204:207], v167 offset:22528
	ds_read_b128 v[208:211], v167 offset:23552
	global_load_lds_dwordx4 v[160:161], off
	s_add_i32 m0, s56, 0x2000
	s_add_u32 s56, s28, 0x200000
	v_lshl_add_u64 v[212:213], s[28:29], 0, v[130:131]
	s_addc_u32 s57, s29, 0
	s_add_i32 s58, s49, s38
	global_load_lds_dwordx4 v[212:213], off
	v_lshl_add_u64 v[214:215], s[56:57], 0, v[128:129]
	s_mov_b32 m0, s58
	v_lshl_add_u64 v[216:217], s[30:31], 0, v[130:131]
	global_load_lds_dwordx4 v[214:215], off
	v_lshl_add_u64 v[214:215], s[56:57], 0, v[130:131]
	s_add_i32 m0, s58, 0x2000
	s_nop 0
	global_load_lds_dwordx4 v[214:215], off
	v_lshl_add_u64 v[214:215], s[30:31], 0, v[128:129]
	s_mov_b32 m0, s25
	s_nop 0
	global_load_lds_dwordx4 v[214:215], off
	s_mov_b32 m0, s40
	s_nop 0
	global_load_lds_dwordx4 v[216:217], off
	s_waitcnt vmcnt(8)
	s_waitcnt lgkmcnt(0)
	s_barrier
	s_waitcnt lgkmcnt(0)
	v_mfma_f32_16x16x32_bf16 v[60:63], v[140:143], v[180:183], v[60:63]
	v_mfma_f32_16x16x32_bf16 v[60:63], v[144:147], v[184:187], v[60:63]
	v_mfma_f32_16x16x32_bf16 v[44:47], v[140:143], v[188:191], v[44:47]
	v_mfma_f32_16x16x32_bf16 v[44:47], v[144:147], v[192:195], v[44:47]
	v_mfma_f32_16x16x32_bf16 v[28:31], v[140:143], v[196:199], v[28:31]
	v_mfma_f32_16x16x32_bf16 v[28:31], v[144:147], v[200:203], v[28:31]
	v_mfma_f32_16x16x32_bf16 v[16:19], v[140:143], v[204:207], v[16:19]
	v_mfma_f32_16x16x32_bf16 v[16:19], v[144:147], v[208:211], v[16:19]
	v_mfma_f32_16x16x32_bf16 v[56:59], v[148:151], v[180:183], v[56:59]
	v_mfma_f32_16x16x32_bf16 v[56:59], v[152:155], v[184:187], v[56:59]
	v_mfma_f32_16x16x32_bf16 v[40:43], v[148:151], v[188:191], v[40:43]
	v_mfma_f32_16x16x32_bf16 v[40:43], v[152:155], v[192:195], v[40:43]
	v_mfma_f32_16x16x32_bf16 v[24:27], v[148:151], v[196:199], v[24:27]
	v_mfma_f32_16x16x32_bf16 v[24:27], v[152:155], v[200:203], v[24:27]
	v_mfma_f32_16x16x32_bf16 v[8:11], v[148:151], v[204:207], v[8:11]
	v_mfma_f32_16x16x32_bf16 v[8:11], v[152:155], v[208:211], v[8:11]
	v_mfma_f32_16x16x32_bf16 v[52:55], v[156:159], v[180:183], v[52:55]
	v_mfma_f32_16x16x32_bf16 v[52:55], v[168:171], v[184:187], v[52:55]
	v_mfma_f32_16x16x32_bf16 v[36:39], v[156:159], v[188:191], v[36:39]
	v_mfma_f32_16x16x32_bf16 v[36:39], v[168:171], v[192:195], v[36:39]
	v_mfma_f32_16x16x32_bf16 v[20:23], v[156:159], v[196:199], v[20:23]
	v_mfma_f32_16x16x32_bf16 v[20:23], v[168:171], v[200:203], v[20:23]
	v_mfma_f32_16x16x32_bf16 v[4:7], v[156:159], v[204:207], v[4:7]
	v_mfma_f32_16x16x32_bf16 v[4:7], v[168:171], v[208:211], v[4:7]
	v_mfma_f32_16x16x32_bf16 v[48:51], v[172:175], v[180:183], v[48:51]
	v_mfma_f32_16x16x32_bf16 v[48:51], v[176:179], v[184:187], v[48:51]
	v_mfma_f32_16x16x32_bf16 v[32:35], v[172:175], v[188:191], v[32:35]
	v_mfma_f32_16x16x32_bf16 v[32:35], v[176:179], v[192:195], v[32:35]
	v_mfma_f32_16x16x32_bf16 v[12:15], v[172:175], v[196:199], v[12:15]
	v_mfma_f32_16x16x32_bf16 v[12:15], v[176:179], v[200:203], v[12:15]
	v_mfma_f32_16x16x32_bf16 v[0:3], v[172:175], v[204:207], v[0:3]
	v_mfma_f32_16x16x32_bf16 v[0:3], v[176:179], v[208:211], v[0:3]
	s_barrier
	s_add_i32 s56, 0, 0x18000
	s_add_i32 s57, 0, 0x1c000
	v_add_u32_e32 v152, s56, v163
	v_add_u32_e32 v176, s57, v163
	ds_read_b128 v[140:143], v152
	ds_read_b128 v[144:147], v152 offset:1024
	ds_read_b128 v[148:151], v152 offset:2048
	ds_read_b128 v[152:155], v152 offset:3072
	ds_read_b128 v[156:159], v176
	ds_read_b128 v[168:171], v176 offset:1024
	ds_read_b128 v[172:175], v176 offset:2048
	ds_read_b128 v[176:179], v176 offset:3072
	s_add_u32 s30, s30, 0x200000
	s_addc_u32 s31, s31, 0
	s_mov_b32 m0, s41
	v_lshl_add_u64 v[218:219], s[30:31], 0, v[128:129]
	ds_read_b128 v[180:183], v167 offset:32768
	ds_read_b128 v[184:187], v167 offset:33792
	ds_read_b128 v[188:191], v167 offset:34816
	ds_read_b128 v[192:195], v167 offset:35840
	ds_read_b128 v[196:199], v167 offset:36864
	ds_read_b128 v[200:203], v167 offset:37888
	ds_read_b128 v[204:207], v167 offset:38912
	ds_read_b128 v[208:211], v167 offset:39936
	global_load_lds_dwordx4 v[218:219], off
	v_lshl_add_u64 v[218:219], s[30:31], 0, v[130:131]
	s_mov_b32 m0, s42
	s_nop 0
	global_load_lds_dwordx4 v[218:219], off
	s_waitcnt vmcnt(8)
	s_waitcnt lgkmcnt(0)
	s_barrier
	s_waitcnt lgkmcnt(0)
	v_mfma_f32_16x16x32_bf16 v[124:127], v[140:143], v[180:183], v[124:127]
	v_mfma_f32_16x16x32_bf16 v[124:127], v[144:147], v[184:187], v[124:127]
	v_mfma_f32_16x16x32_bf16 v[108:111], v[140:143], v[188:191], v[108:111]
	v_mfma_f32_16x16x32_bf16 v[108:111], v[144:147], v[192:195], v[108:111]
	v_mfma_f32_16x16x32_bf16 v[92:95], v[140:143], v[196:199], v[92:95]
	v_mfma_f32_16x16x32_bf16 v[92:95], v[144:147], v[200:203], v[92:95]
	v_mfma_f32_16x16x32_bf16 v[76:79], v[140:143], v[204:207], v[76:79]
	v_mfma_f32_16x16x32_bf16 v[76:79], v[144:147], v[208:211], v[76:79]
	v_mfma_f32_16x16x32_bf16 v[120:123], v[148:151], v[180:183], v[120:123]
	v_mfma_f32_16x16x32_bf16 v[120:123], v[152:155], v[184:187], v[120:123]
	v_mfma_f32_16x16x32_bf16 v[104:107], v[148:151], v[188:191], v[104:107]
	v_mfma_f32_16x16x32_bf16 v[104:107], v[152:155], v[192:195], v[104:107]
	v_mfma_f32_16x16x32_bf16 v[88:91], v[148:151], v[196:199], v[88:91]
	v_mfma_f32_16x16x32_bf16 v[88:91], v[152:155], v[200:203], v[88:91]
	v_mfma_f32_16x16x32_bf16 v[72:75], v[148:151], v[204:207], v[72:75]
	v_mfma_f32_16x16x32_bf16 v[72:75], v[152:155], v[208:211], v[72:75]
	v_mfma_f32_16x16x32_bf16 v[116:119], v[156:159], v[180:183], v[116:119]
	v_mfma_f32_16x16x32_bf16 v[116:119], v[168:171], v[184:187], v[116:119]
	v_mfma_f32_16x16x32_bf16 v[100:103], v[156:159], v[188:191], v[100:103]
	v_mfma_f32_16x16x32_bf16 v[100:103], v[168:171], v[192:195], v[100:103]
	v_mfma_f32_16x16x32_bf16 v[84:87], v[156:159], v[196:199], v[84:87]
	v_mfma_f32_16x16x32_bf16 v[84:87], v[168:171], v[200:203], v[84:87]
	v_mfma_f32_16x16x32_bf16 v[68:71], v[156:159], v[204:207], v[68:71]
	v_mfma_f32_16x16x32_bf16 v[68:71], v[168:171], v[208:211], v[68:71]
	v_mfma_f32_16x16x32_bf16 v[112:115], v[172:175], v[180:183], v[112:115]
	v_mfma_f32_16x16x32_bf16 v[112:115], v[176:179], v[184:187], v[112:115]
	v_mfma_f32_16x16x32_bf16 v[96:99], v[172:175], v[188:191], v[96:99]
	v_mfma_f32_16x16x32_bf16 v[96:99], v[176:179], v[192:195], v[96:99]
	v_mfma_f32_16x16x32_bf16 v[80:83], v[172:175], v[196:199], v[80:83]
	v_mfma_f32_16x16x32_bf16 v[80:83], v[176:179], v[200:203], v[80:83]
	v_mfma_f32_16x16x32_bf16 v[64:67], v[172:175], v[204:207], v[64:67]
	v_mfma_f32_16x16x32_bf16 v[64:67], v[176:179], v[208:211], v[64:67]
	s_barrier
	s_add_i32 s30, s56, s38
	v_lshl_add_u64 v[160:161], v[160:161], 0, s[10:11]
	s_mov_b32 m0, s30
	ds_read_b128 v[180:183], v167 offset:49152
	ds_read_b128 v[184:187], v167 offset:50176
	ds_read_b128 v[188:191], v167 offset:51200
	ds_read_b128 v[192:195], v167 offset:52224
	ds_read_b128 v[196:199], v167 offset:53248
	ds_read_b128 v[200:203], v167 offset:54272
	ds_read_b128 v[204:207], v167 offset:55296
	ds_read_b128 v[208:211], v167 offset:56320
	global_load_lds_dwordx4 v[160:161], off
	s_add_i32 m0, s30, 0x2000
	s_add_u32 s28, s28, 0x200080
	v_lshl_add_u64 v[160:161], v[212:213], 0, s[10:11]
	s_addc_u32 s29, s29, 0
	s_add_i32 s30, s57, s38
	global_load_lds_dwordx4 v[160:161], off
	v_lshl_add_u64 v[160:161], s[28:29], 0, v[128:129]
	s_mov_b32 m0, s30
	s_nop 0
	global_load_lds_dwordx4 v[160:161], off
	v_lshl_add_u64 v[160:161], s[28:29], 0, v[130:131]
	s_add_i32 m0, s30, 0x2000
	s_nop 0
	global_load_lds_dwordx4 v[160:161], off
	v_lshl_add_u64 v[160:161], v[214:215], 0, s[10:11]
	s_mov_b32 m0, s45
	s_nop 0
	global_load_lds_dwordx4 v[160:161], off
	v_lshl_add_u64 v[160:161], v[216:217], 0, s[10:11]
	s_mov_b32 m0, s46
	s_nop 0
	global_load_lds_dwordx4 v[160:161], off
	s_waitcnt vmcnt(8)
	s_waitcnt lgkmcnt(0)
	s_barrier
	s_waitcnt lgkmcnt(0)
	v_mfma_f32_16x16x32_bf16 v[60:63], v[140:143], v[180:183], v[60:63]
	v_mfma_f32_16x16x32_bf16 v[60:63], v[144:147], v[184:187], v[60:63]
	v_mfma_f32_16x16x32_bf16 v[44:47], v[140:143], v[188:191], v[44:47]
	v_mfma_f32_16x16x32_bf16 v[44:47], v[144:147], v[192:195], v[44:47]
	v_mfma_f32_16x16x32_bf16 v[28:31], v[140:143], v[196:199], v[28:31]
	v_mfma_f32_16x16x32_bf16 v[28:31], v[144:147], v[200:203], v[28:31]
	v_mfma_f32_16x16x32_bf16 v[16:19], v[140:143], v[204:207], v[16:19]
	v_mfma_f32_16x16x32_bf16 v[16:19], v[144:147], v[208:211], v[16:19]
	v_mfma_f32_16x16x32_bf16 v[56:59], v[148:151], v[180:183], v[56:59]
	v_mfma_f32_16x16x32_bf16 v[56:59], v[152:155], v[184:187], v[56:59]
	v_mfma_f32_16x16x32_bf16 v[40:43], v[148:151], v[188:191], v[40:43]
	v_mfma_f32_16x16x32_bf16 v[40:43], v[152:155], v[192:195], v[40:43]
	v_mfma_f32_16x16x32_bf16 v[24:27], v[148:151], v[196:199], v[24:27]
	v_mfma_f32_16x16x32_bf16 v[24:27], v[152:155], v[200:203], v[24:27]
	v_mfma_f32_16x16x32_bf16 v[8:11], v[148:151], v[204:207], v[8:11]
	v_mfma_f32_16x16x32_bf16 v[8:11], v[152:155], v[208:211], v[8:11]
	v_mfma_f32_16x16x32_bf16 v[52:55], v[156:159], v[180:183], v[52:55]
	v_mfma_f32_16x16x32_bf16 v[52:55], v[168:171], v[184:187], v[52:55]
	v_mfma_f32_16x16x32_bf16 v[36:39], v[156:159], v[188:191], v[36:39]
	v_mfma_f32_16x16x32_bf16 v[36:39], v[168:171], v[192:195], v[36:39]
	v_mfma_f32_16x16x32_bf16 v[20:23], v[156:159], v[196:199], v[20:23]
	v_mfma_f32_16x16x32_bf16 v[20:23], v[168:171], v[200:203], v[20:23]
	v_mfma_f32_16x16x32_bf16 v[4:7], v[156:159], v[204:207], v[4:7]
	v_mfma_f32_16x16x32_bf16 v[4:7], v[168:171], v[208:211], v[4:7]
	v_mfma_f32_16x16x32_bf16 v[48:51], v[172:175], v[180:183], v[48:51]
	v_mfma_f32_16x16x32_bf16 v[48:51], v[176:179], v[184:187], v[48:51]
	v_mfma_f32_16x16x32_bf16 v[32:35], v[172:175], v[188:191], v[32:35]
	v_mfma_f32_16x16x32_bf16 v[32:35], v[176:179], v[192:195], v[32:35]
	v_mfma_f32_16x16x32_bf16 v[12:15], v[172:175], v[196:199], v[12:15]
	v_mfma_f32_16x16x32_bf16 v[12:15], v[176:179], v[200:203], v[12:15]
	v_mfma_f32_16x16x32_bf16 v[0:3], v[172:175], v[204:207], v[0:3]
	v_mfma_f32_16x16x32_bf16 v[0:3], v[176:179], v[208:211], v[0:3]
	s_barrier
	s_add_i32 s55, s55, 2
	s_add_u32 s26, s26, 0x100
	s_addc_u32 s27, s27, 0
	s_add_u32 s53, s53, 0x100
	s_addc_u32 s54, s54, 0
	s_cmpk_gt_u32 s55, 0x7d
	s_cbranch_scc0 .LBB0_1098
	s_and_b64 vcc, exec, s[14:15]
	s_cbranch_vccz .LBB0_1101
	s_barrier
